# down GEMM streams K from the end (the ACT columns the FFN-up phase wrote last are still in L2)
# baseline (speedup 1.0000x reference)
.Ldn_afdone:
	s_barrier
	s_lshr_b32 s1, s78, 2
	s_lshl_b32 s1, s1, 7
	s_lshl_b32 s2, s0, 8
	s_mul_i32 s3, s2, 0x1600
	s_add_u32 s68, s18, s3
	s_addc_u32 s69, s19, 0
	s_mul_i32 s3, s1, 0x1600
	s_add_u32 s70, s80, s3
	s_addc_u32 s71, s81, 0
	s_add_u32 s68, s68, 0x1580
	s_addc_u32 s69, s69, 0
	s_add_u32 s70, s70, 0x1580
	s_addc_u32 s71, s71, 0
	s_lshl_b32 s3, s2, 11
	s_lshl_b32 s12, s1, 1
	s_add_u32 s3, s3, s12
	s_add_u32 s74, s24, s3
	s_addc_u32 s75, s25, 0
	s_add_i32 s12, s0, -12
	s_lshr_b32 s12, s12, 2
	s_cmp_lt_u32 s0, 16
	s_cselect_b32 s12, 0, s12
	s_cselect_b32 s14, s52, s54
	s_cselect_b32 s15, s53, s55
	s_mul_i32 s13, s82, 5
	s_add_i32 s12, s12, s13
	s_mul_i32 s12, s12, 0x6000
	s_add_u32 s12, s12, 0x5000
	s_lshl_b32 s13, s1, 2
	s_add_u32 s12, s12, s13
	s_add_u32 s72, s30, s12
	s_addc_u32 s73, s31, 0
	s_and_b32 s12, s0, 15
	s_lshl_b32 s12, s12, 20
	s_add_u32 s12, s12, s13
	s_add_u32 s14, s14, s12
	s_addc_u32 s15, s15, 0
	s_add_u32 m0, s76, 0x0
	s_nop 0
	global_load_lds_dwordx4 v196, s[68:69]
	s_add_u32 m0, s76, 0x2000
	s_nop 0
	global_load_lds_dwordx4 v197, s[68:69]
	s_add_u32 m0, s76, 0x4000
	s_nop 0
	global_load_lds_dwordx4 v198, s[68:69]
	s_add_u32 m0, s76, 0x6000
	s_nop 0
	global_load_lds_dwordx4 v199, s[68:69]
	s_add_u32 m0, s76, 0x8000
	s_nop 0
	global_load_lds_dwordx4 v196, s[70:71]
	s_add_u32 m0, s76, 0xa000
	s_nop 0
	global_load_lds_dwordx4 v197, s[70:71]
	s_sub_u32 s68, s68, 0x80
	s_subb_u32 s69, s69, 0
	s_sub_u32 s70, s70, 0x80
	s_subb_u32 s71, s71, 0
	s_add_u32 m0, s76, 0xc000
	s_nop 0
	global_load_lds_dwordx4 v196, s[68:69]
	s_add_u32 m0, s76, 0xe000
	s_nop 0
	global_load_lds_dwordx4 v197, s[68:69]
	s_add_u32 m0, s76, 0x10000
	s_nop 0
	global_load_lds_dwordx4 v198, s[68:69]
	s_add_u32 m0, s76, 0x12000
	s_nop 0
	global_load_lds_dwordx4 v199, s[68:69]
	s_add_u32 m0, s76, 0x14000
	s_nop 0
	global_load_lds_dwordx4 v196, s[70:71]
	s_add_u32 m0, s76, 0x16000
	s_nop 0
	global_load_lds_dwordx4 v197, s[70:71]
	s_sub_u32 s68, s68, 0x80
	s_subb_u32 s69, s69, 0
	s_sub_u32 s70, s70, 0x80
	s_subb_u32 s71, s71, 0
	s_waitcnt vmcnt(6)
	s_barrier
	s_cmp_ge_u32 s76, 0x1000
	s_cbranch_scc1 .Ldn_streamB
	v_add_u32_e32 v204, 0x0, v200
	v_add_u32_e32 v205, 0x0, v202
	ds_read_b128 v[130:133], v204 offset:0
	ds_read_b128 v[134:137], v204 offset:2048
	ds_read_b128 v[138:141], v204 offset:4096
	ds_read_b128 v[142:145], v204 offset:6144
	ds_read_b128 v[146:149], v205 offset:0
	ds_read_b128 v[150:153], v205 offset:2048
	ds_read_b128 v[154:157], v205 offset:4096
	ds_read_b128 v[158:161], v205 offset:6144
	v_add_u32_e32 v204, 0x0, v201
	v_add_u32_e32 v205, 0x0, v203
	ds_read_b128 v[212:215], v204 offset:0
	ds_read_b128 v[216:219], v204 offset:2048
	ds_read_b128 v[220:223], v204 offset:4096
	ds_read_b128 v[224:227], v204 offset:6144
	ds_read_b128 v[228:231], v205 offset:0
	ds_read_b128 v[232:235], v205 offset:2048
	ds_read_b128 v[236:239], v205 offset:4096
	ds_read_b128 v[240:243], v205 offset:6144
	s_add_u32 m0, s76, 0x18000
	s_nop 0
	global_load_lds_dwordx4 v196, s[68:69]
	s_add_u32 m0, s76, 0x1a000
	s_nop 0
	global_load_lds_dwordx4 v197, s[68:69]
	s_add_u32 m0, s76, 0x1c000
	s_nop 0
	global_load_lds_dwordx4 v198, s[68:69]
	s_add_u32 m0, s76, 0x1e000
	s_nop 0
	global_load_lds_dwordx4 v199, s[68:69]
	s_add_u32 m0, s76, 0x20000
	s_nop 0
	global_load_lds_dwordx4 v196, s[70:71]
	s_add_u32 m0, s76, 0x22000
	s_nop 0
	global_load_lds_dwordx4 v197, s[70:71]
	s_sub_u32 s68, s68, 0x80
	s_subb_u32 s69, s69, 0
	s_sub_u32 s70, s70, 0x80
	s_subb_u32 s71, s71, 0
	global_load_dwordx4 v[174:177], v190, s[72:73] offset:0
	global_load_dwordx4 v[178:181], v190, s[72:73] offset:64
	global_load_dwordx4 v[182:185], v190, s[72:73] offset:128
	global_load_dwordx4 v[186:189], v190, s[72:73] offset:192
	global_load_dwordx2 v[66:67], v206, s[74:75] offset:0
	global_load_dwordx2 v[70:71], v206, s[74:75] offset:32
	global_load_dwordx2 v[74:75], v206, s[74:75] offset:64
	s_waitcnt lgkmcnt(0)
	s_barrier
	v_mfma_f32_16x16x32_bf16 v[2:5], v[146:149], v[130:133], 0
	v_mfma_f32_16x16x32_bf16 v[6:9], v[150:153], v[130:133], 0
	v_mfma_f32_16x16x32_bf16 v[10:13], v[154:157], v[130:133], 0
	v_mfma_f32_16x16x32_bf16 v[14:17], v[158:161], v[130:133], 0
	v_mfma_f32_16x16x32_bf16 v[18:21], v[146:149], v[134:137], 0
	v_mfma_f32_16x16x32_bf16 v[22:25], v[150:153], v[134:137], 0
	v_mfma_f32_16x16x32_bf16 v[26:29], v[154:157], v[134:137], 0
	v_mfma_f32_16x16x32_bf16 v[30:33], v[158:161], v[134:137], 0
	v_mfma_f32_16x16x32_bf16 v[34:37], v[146:149], v[138:141], 0
	v_mfma_f32_16x16x32_bf16 v[38:41], v[150:153], v[138:141], 0
	v_mfma_f32_16x16x32_bf16 v[42:45], v[154:157], v[138:141], 0
	v_mfma_f32_16x16x32_bf16 v[46:49], v[158:161], v[138:141], 0
	v_mfma_f32_16x16x32_bf16 v[50:53], v[146:149], v[142:145], 0
	v_mfma_f32_16x16x32_bf16 v[54:57], v[150:153], v[142:145], 0
	v_mfma_f32_16x16x32_bf16 v[58:61], v[154:157], v[142:145], 0
	v_mfma_f32_16x16x32_bf16 v[62:65], v[158:161], v[142:145], 0
	v_mfma_f32_16x16x32_bf16 v[2:5], v[228:231], v[212:215], v[2:5]
	v_mfma_f32_16x16x32_bf16 v[6:9], v[232:235], v[212:215], v[6:9]
	v_mfma_f32_16x16x32_bf16 v[10:13], v[236:239], v[212:215], v[10:13]
	v_mfma_f32_16x16x32_bf16 v[14:17], v[240:243], v[212:215], v[14:17]
	v_mfma_f32_16x16x32_bf16 v[18:21], v[228:231], v[216:219], v[18:21]
	v_mfma_f32_16x16x32_bf16 v[22:25], v[232:235], v[216:219], v[22:25]
	v_mfma_f32_16x16x32_bf16 v[26:29], v[236:239], v[216:219], v[26:29]
	v_mfma_f32_16x16x32_bf16 v[30:33], v[240:243], v[216:219], v[30:33]
	v_mfma_f32_16x16x32_bf16 v[34:37], v[228:231], v[220:223], v[34:37]
	v_mfma_f32_16x16x32_bf16 v[38:41], v[232:235], v[220:223], v[38:41]
	v_mfma_f32_16x16x32_bf16 v[42:45], v[236:239], v[220:223], v[42:45]
	v_mfma_f32_16x16x32_bf16 v[46:49], v[240:243], v[220:223], v[46:49]
	v_mfma_f32_16x16x32_bf16 v[50:53], v[228:231], v[224:227], v[50:53]
	v_mfma_f32_16x16x32_bf16 v[54:57], v[232:235], v[224:227], v[54:57]
	v_mfma_f32_16x16x32_bf16 v[58:61], v[236:239], v[224:227], v[58:61]
	v_mfma_f32_16x16x32_bf16 v[62:65], v[240:243], v[224:227], v[62:65]
	s_waitcnt vmcnt(13)
	s_barrier
	v_add_u32_e32 v204, 0xc000, v200
	v_add_u32_e32 v205, 0xc000, v202
	ds_read_b128 v[130:133], v204 offset:0
	ds_read_b128 v[134:137], v204 offset:2048
	ds_read_b128 v[138:141], v204 offset:4096
	ds_read_b128 v[142:145], v204 offset:6144
	ds_read_b128 v[146:149], v205 offset:0
	ds_read_b128 v[150:153], v205 offset:2048
	ds_read_b128 v[154:157], v205 offset:4096
	ds_read_b128 v[158:161], v205 offset:6144
	v_add_u32_e32 v204, 0xc000, v201
	v_add_u32_e32 v205, 0xc000, v203
	ds_read_b128 v[212:215], v204 offset:0
	ds_read_b128 v[216:219], v204 offset:2048
	ds_read_b128 v[220:223], v204 offset:4096
	ds_read_b128 v[224:227], v204 offset:6144
	ds_read_b128 v[228:231], v205 offset:0
	ds_read_b128 v[232:235], v205 offset:2048
	ds_read_b128 v[236:239], v205 offset:4096
	ds_read_b128 v[240:243], v205 offset:6144
	s_add_u32 m0, s76, 0x0
	s_nop 0
	global_load_lds_dwordx4 v196, s[68:69]
	s_add_u32 m0, s76, 0x2000
	s_nop 0
	global_load_lds_dwordx4 v197, s[68:69]
	s_add_u32 m0, s76, 0x4000
	s_nop 0
	global_load_lds_dwordx4 v198, s[68:69]
	s_add_u32 m0, s76, 0x6000
	s_nop 0
	global_load_lds_dwordx4 v199, s[68:69]
	s_add_u32 m0, s76, 0x8000
	s_nop 0
	global_load_lds_dwordx4 v196, s[70:71]
	s_add_u32 m0, s76, 0xa000
	s_nop 0
	global_load_lds_dwordx4 v197, s[70:71]
	s_sub_u32 s68, s68, 0x80
	s_subb_u32 s69, s69, 0
	s_sub_u32 s70, s70, 0x80
	s_subb_u32 s71, s71, 0
	global_load_dwordx2 v[78:79], v206, s[74:75] offset:96
	global_load_dwordx2 v[82:83], v207, s[74:75] offset:0
	global_load_dwordx2 v[86:87], v207, s[74:75] offset:32
	global_load_dwordx2 v[90:91], v207, s[74:75] offset:64
	global_load_dwordx2 v[94:95], v207, s[74:75] offset:96
	global_load_dwordx2 v[98:99], v208, s[74:75] offset:0
	global_load_dwordx2 v[102:103], v208, s[74:75] offset:32
	s_waitcnt lgkmcnt(0)
	s_barrier
	v_mfma_f32_16x16x32_bf16 v[2:5], v[146:149], v[130:133], v[2:5]
	v_mfma_f32_16x16x32_bf16 v[6:9], v[150:153], v[130:133], v[6:9]
	v_mfma_f32_16x16x32_bf16 v[10:13], v[154:157], v[130:133], v[10:13]
	v_mfma_f32_16x16x32_bf16 v[14:17], v[158:161], v[130:133], v[14:17]
	v_mfma_f32_16x16x32_bf16 v[18:21], v[146:149], v[134:137], v[18:21]
	v_mfma_f32_16x16x32_bf16 v[22:25], v[150:153], v[134:137], v[22:25]
	v_mfma_f32_16x16x32_bf16 v[26:29], v[154:157], v[134:137], v[26:29]
	v_mfma_f32_16x16x32_bf16 v[30:33], v[158:161], v[134:137], v[30:33]
	v_mfma_f32_16x16x32_bf16 v[34:37], v[146:149], v[138:141], v[34:37]
	v_mfma_f32_16x16x32_bf16 v[38:41], v[150:153], v[138:141], v[38:41]
	v_mfma_f32_16x16x32_bf16 v[42:45], v[154:157], v[138:141], v[42:45]
	v_mfma_f32_16x16x32_bf16 v[46:49], v[158:161], v[138:141], v[46:49]
	v_mfma_f32_16x16x32_bf16 v[50:53], v[146:149], v[142:145], v[50:53]
	v_mfma_f32_16x16x32_bf16 v[54:57], v[150:153], v[142:145], v[54:57]
	v_mfma_f32_16x16x32_bf16 v[58:61], v[154:157], v[142:145], v[58:61]
	v_mfma_f32_16x16x32_bf16 v[62:65], v[158:161], v[142:145], v[62:65]
	v_mfma_f32_16x16x32_bf16 v[2:5], v[228:231], v[212:215], v[2:5]
	v_mfma_f32_16x16x32_bf16 v[6:9], v[232:235], v[212:215], v[6:9]
	v_mfma_f32_16x16x32_bf16 v[10:13], v[236:239], v[212:215], v[10:13]
	v_mfma_f32_16x16x32_bf16 v[14:17], v[240:243], v[212:215], v[14:17]
	v_mfma_f32_16x16x32_bf16 v[18:21], v[228:231], v[216:219], v[18:21]
	v_mfma_f32_16x16x32_bf16 v[22:25], v[232:235], v[216:219], v[22:25]
	v_mfma_f32_16x16x32_bf16 v[26:29], v[236:239], v[216:219], v[26:29]
	v_mfma_f32_16x16x32_bf16 v[30:33], v[240:243], v[216:219], v[30:33]
	v_mfma_f32_16x16x32_bf16 v[34:37], v[228:231], v[220:223], v[34:37]
	v_mfma_f32_16x16x32_bf16 v[38:41], v[232:235], v[220:223], v[38:41]
	v_mfma_f32_16x16x32_bf16 v[42:45], v[236:239], v[220:223], v[42:45]
	v_mfma_f32_16x16x32_bf16 v[46:49], v[240:243], v[220:223], v[46:49]
	v_mfma_f32_16x16x32_bf16 v[50:53], v[228:231], v[224:227], v[50:53]
	v_mfma_f32_16x16x32_bf16 v[54:57], v[232:235], v[224:227], v[54:57]
	v_mfma_f32_16x16x32_bf16 v[58:61], v[236:239], v[224:227], v[58:61]
	v_mfma_f32_16x16x32_bf16 v[62:65], v[240:243], v[224:227], v[62:65]
	s_waitcnt vmcnt(20)
	s_barrier
	v_add_u32_e32 v204, 0x18000, v200
	v_add_u32_e32 v205, 0x18000, v202
	ds_read_b128 v[130:133], v204 offset:0
	ds_read_b128 v[134:137], v204 offset:2048
	ds_read_b128 v[138:141], v204 offset:4096
	ds_read_b128 v[142:145], v204 offset:6144
	ds_read_b128 v[146:149], v205 offset:0
	ds_read_b128 v[150:153], v205 offset:2048
	ds_read_b128 v[154:157], v205 offset:4096
	ds_read_b128 v[158:161], v205 offset:6144
	v_add_u32_e32 v204, 0x18000, v201
	v_add_u32_e32 v205, 0x18000, v203
	ds_read_b128 v[212:215], v204 offset:0
	ds_read_b128 v[216:219], v204 offset:2048
	ds_read_b128 v[220:223], v204 offset:4096
	ds_read_b128 v[224:227], v204 offset:6144
	ds_read_b128 v[228:231], v205 offset:0
	ds_read_b128 v[232:235], v205 offset:2048
	ds_read_b128 v[236:239], v205 offset:4096
	ds_read_b128 v[240:243], v205 offset:6144
	s_add_u32 m0, s76, 0xc000
	s_nop 0
	global_load_lds_dwordx4 v196, s[68:69]
	s_add_u32 m0, s76, 0xe000
	s_nop 0
	global_load_lds_dwordx4 v197, s[68:69]
	s_add_u32 m0, s76, 0x10000
	s_nop 0
	global_load_lds_dwordx4 v198, s[68:69]
	s_add_u32 m0, s76, 0x12000
	s_nop 0
	global_load_lds_dwordx4 v199, s[68:69]
	s_add_u32 m0, s76, 0x14000
	s_nop 0
	global_load_lds_dwordx4 v196, s[70:71]
	s_add_u32 m0, s76, 0x16000
	s_nop 0
	global_load_lds_dwordx4 v197, s[70:71]
	s_sub_u32 s68, s68, 0x80
	s_subb_u32 s69, s69, 0
	s_sub_u32 s70, s70, 0x80
	s_subb_u32 s71, s71, 0
	global_load_dwordx2 v[106:107], v208, s[74:75] offset:64
	global_load_dwordx2 v[110:111], v208, s[74:75] offset:96
	global_load_dwordx2 v[114:115], v209, s[74:75] offset:0
	global_load_dwordx2 v[118:119], v209, s[74:75] offset:32
	global_load_dwordx2 v[122:123], v209, s[74:75] offset:64
	global_load_dwordx2 v[126:127], v209, s[74:75] offset:96
	s_waitcnt lgkmcnt(0)
	s_barrier
	v_mfma_f32_16x16x32_bf16 v[2:5], v[146:149], v[130:133], v[2:5]
	v_mfma_f32_16x16x32_bf16 v[6:9], v[150:153], v[130:133], v[6:9]
	v_mfma_f32_16x16x32_bf16 v[10:13], v[154:157], v[130:133], v[10:13]
	v_mfma_f32_16x16x32_bf16 v[14:17], v[158:161], v[130:133], v[14:17]
	v_mfma_f32_16x16x32_bf16 v[18:21], v[146:149], v[134:137], v[18:21]
	v_mfma_f32_16x16x32_bf16 v[22:25], v[150:153], v[134:137], v[22:25]
	v_mfma_f32_16x16x32_bf16 v[26:29], v[154:157], v[134:137], v[26:29]
	v_mfma_f32_16x16x32_bf16 v[30:33], v[158:161], v[134:137], v[30:33]
	v_mfma_f32_16x16x32_bf16 v[34:37], v[146:149], v[138:141], v[34:37]
	v_mfma_f32_16x16x32_bf16 v[38:41], v[150:153], v[138:141], v[38:41]
	v_mfma_f32_16x16x32_bf16 v[42:45], v[154:157], v[138:141], v[42:45]
	v_mfma_f32_16x16x32_bf16 v[46:49], v[158:161], v[138:141], v[46:49]
	v_mfma_f32_16x16x32_bf16 v[50:53], v[146:149], v[142:145], v[50:53]
	v_mfma_f32_16x16x32_bf16 v[54:57], v[150:153], v[142:145], v[54:57]
	v_mfma_f32_16x16x32_bf16 v[58:61], v[154:157], v[142:145], v[58:61]
	v_mfma_f32_16x16x32_bf16 v[62:65], v[158:161], v[142:145], v[62:65]
	v_mfma_f32_16x16x32_bf16 v[2:5], v[228:231], v[212:215], v[2:5]
	v_mfma_f32_16x16x32_bf16 v[6:9], v[232:235], v[212:215], v[6:9]
	v_mfma_f32_16x16x32_bf16 v[10:13], v[236:239], v[212:215], v[10:13]
	v_mfma_f32_16x16x32_bf16 v[14:17], v[240:243], v[212:215], v[14:17]
	v_mfma_f32_16x16x32_bf16 v[18:21], v[228:231], v[216:219], v[18:21]
	v_mfma_f32_16x16x32_bf16 v[22:25], v[232:235], v[216:219], v[22:25]
	v_mfma_f32_16x16x32_bf16 v[26:29], v[236:239], v[216:219], v[26:29]
	v_mfma_f32_16x16x32_bf16 v[30:33], v[240:243], v[216:219], v[30:33]
	v_mfma_f32_16x16x32_bf16 v[34:37], v[228:231], v[220:223], v[34:37]
	v_mfma_f32_16x16x32_bf16 v[38:41], v[232:235], v[220:223], v[38:41]
	v_mfma_f32_16x16x32_bf16 v[42:45], v[236:239], v[220:223], v[42:45]
	v_mfma_f32_16x16x32_bf16 v[46:49], v[240:243], v[220:223], v[46:49]
	v_mfma_f32_16x16x32_bf16 v[50:53], v[228:231], v[224:227], v[50:53]
	v_mfma_f32_16x16x32_bf16 v[54:57], v[232:235], v[224:227], v[54:57]
	v_mfma_f32_16x16x32_bf16 v[58:61], v[236:239], v[224:227], v[58:61]
	v_mfma_f32_16x16x32_bf16 v[62:65], v[240:243], v[224:227], v[62:65]
	s_waitcnt vmcnt(19)
	s_barrier
	v_add_u32_e32 v204, 0x0, v200
	v_add_u32_e32 v205, 0x0, v202
	ds_read_b128 v[130:133], v204 offset:0
	ds_read_b128 v[134:137], v204 offset:2048
	ds_read_b128 v[138:141], v204 offset:4096
	ds_read_b128 v[142:145], v204 offset:6144
	ds_read_b128 v[146:149], v205 offset:0
	ds_read_b128 v[150:153], v205 offset:2048
	ds_read_b128 v[154:157], v205 offset:4096
	ds_read_b128 v[158:161], v205 offset:6144
	v_add_u32_e32 v204, 0x0, v201
	v_add_u32_e32 v205, 0x0, v203
	ds_read_b128 v[212:215], v204 offset:0
	ds_read_b128 v[216:219], v204 offset:2048
	ds_read_b128 v[220:223], v204 offset:4096
	ds_read_b128 v[224:227], v204 offset:6144
	ds_read_b128 v[228:231], v205 offset:0
	ds_read_b128 v[232:235], v205 offset:2048
	ds_read_b128 v[236:239], v205 offset:4096
	ds_read_b128 v[240:243], v205 offset:6144
	s_add_u32 m0, s76, 0x18000
	s_nop 0
	global_load_lds_dwordx4 v196, s[68:69]
	s_add_u32 m0, s76, 0x1a000
	s_nop 0
	global_load_lds_dwordx4 v197, s[68:69]
	s_add_u32 m0, s76, 0x1c000
	s_nop 0
	global_load_lds_dwordx4 v198, s[68:69]
	s_add_u32 m0, s76, 0x1e000
	s_nop 0
	global_load_lds_dwordx4 v199, s[68:69]
	s_add_u32 m0, s76, 0x20000
	s_nop 0
	global_load_lds_dwordx4 v196, s[70:71]
	s_add_u32 m0, s76, 0x22000
	s_nop 0
	global_load_lds_dwordx4 v197, s[70:71]
	s_sub_u32 s68, s68, 0x80
	s_subb_u32 s69, s69, 0
	s_sub_u32 s70, s70, 0x80
	s_subb_u32 s71, s71, 0
	s_waitcnt lgkmcnt(0)
	s_barrier
	v_mfma_f32_16x16x32_bf16 v[2:5], v[146:149], v[130:133], v[2:5]
	v_mfma_f32_16x16x32_bf16 v[6:9], v[150:153], v[130:133], v[6:9]
	v_mfma_f32_16x16x32_bf16 v[10:13], v[154:157], v[130:133], v[10:13]
	v_mfma_f32_16x16x32_bf16 v[14:17], v[158:161], v[130:133], v[14:17]
	v_mfma_f32_16x16x32_bf16 v[18:21], v[146:149], v[134:137], v[18:21]
	v_mfma_f32_16x16x32_bf16 v[22:25], v[150:153], v[134:137], v[22:25]
	v_mfma_f32_16x16x32_bf16 v[26:29], v[154:157], v[134:137], v[26:29]
	v_mfma_f32_16x16x32_bf16 v[30:33], v[158:161], v[134:137], v[30:33]
	v_mfma_f32_16x16x32_bf16 v[34:37], v[146:149], v[138:141], v[34:37]
	v_mfma_f32_16x16x32_bf16 v[38:41], v[150:153], v[138:141], v[38:41]
	v_mfma_f32_16x16x32_bf16 v[42:45], v[154:157], v[138:141], v[42:45]
	v_mfma_f32_16x16x32_bf16 v[46:49], v[158:161], v[138:141], v[46:49]
	v_mfma_f32_16x16x32_bf16 v[50:53], v[146:149], v[142:145], v[50:53]
	v_mfma_f32_16x16x32_bf16 v[54:57], v[150:153], v[142:145], v[54:57]
	v_mfma_f32_16x16x32_bf16 v[58:61], v[154:157], v[142:145], v[58:61]
	v_mfma_f32_16x16x32_bf16 v[62:65], v[158:161], v[142:145], v[62:65]
	v_mfma_f32_16x16x32_bf16 v[2:5], v[228:231], v[212:215], v[2:5]
	v_mfma_f32_16x16x32_bf16 v[6:9], v[232:235], v[212:215], v[6:9]
	v_mfma_f32_16x16x32_bf16 v[10:13], v[236:239], v[212:215], v[10:13]
	v_mfma_f32_16x16x32_bf16 v[14:17], v[240:243], v[212:215], v[14:17]
	v_mfma_f32_16x16x32_bf16 v[18:21], v[228:231], v[216:219], v[18:21]
	v_mfma_f32_16x16x32_bf16 v[22:25], v[232:235], v[216:219], v[22:25]
	v_mfma_f32_16x16x32_bf16 v[26:29], v[236:239], v[216:219], v[26:29]
	v_mfma_f32_16x16x32_bf16 v[30:33], v[240:243], v[216:219], v[30:33]
	v_mfma_f32_16x16x32_bf16 v[34:37], v[228:231], v[220:223], v[34:37]
	v_mfma_f32_16x16x32_bf16 v[38:41], v[232:235], v[220:223], v[38:41]
	v_mfma_f32_16x16x32_bf16 v[42:45], v[236:239], v[220:223], v[42:45]
	v_mfma_f32_16x16x32_bf16 v[46:49], v[240:243], v[220:223], v[46:49]
	v_mfma_f32_16x16x32_bf16 v[50:53], v[228:231], v[224:227], v[50:53]
	v_mfma_f32_16x16x32_bf16 v[54:57], v[232:235], v[224:227], v[54:57]
	v_mfma_f32_16x16x32_bf16 v[58:61], v[236:239], v[224:227], v[58:61]
	v_mfma_f32_16x16x32_bf16 v[62:65], v[240:243], v[224:227], v[62:65]
	s_waitcnt vmcnt(12)
	s_barrier
	v_add_u32_e32 v204, 0xc000, v200
	v_add_u32_e32 v205, 0xc000, v202
	ds_read_b128 v[130:133], v204 offset:0
	ds_read_b128 v[134:137], v204 offset:2048
	ds_read_b128 v[138:141], v204 offset:4096
	ds_read_b128 v[142:145], v204 offset:6144
	ds_read_b128 v[146:149], v205 offset:0
	ds_read_b128 v[150:153], v205 offset:2048
	ds_read_b128 v[154:157], v205 offset:4096
	ds_read_b128 v[158:161], v205 offset:6144
	v_add_u32_e32 v204, 0xc000, v201
	v_add_u32_e32 v205, 0xc000, v203
	ds_read_b128 v[212:215], v204 offset:0
	ds_read_b128 v[216:219], v204 offset:2048
	ds_read_b128 v[220:223], v204 offset:4096
	ds_read_b128 v[224:227], v204 offset:6144
	ds_read_b128 v[228:231], v205 offset:0
	ds_read_b128 v[232:235], v205 offset:2048
	ds_read_b128 v[236:239], v205 offset:4096
	ds_read_b128 v[240:243], v205 offset:6144
	s_add_u32 m0, s76, 0x0
	s_nop 0
	global_load_lds_dwordx4 v196, s[68:69]
	s_add_u32 m0, s76, 0x2000
	s_nop 0
	global_load_lds_dwordx4 v197, s[68:69]
	s_add_u32 m0, s76, 0x4000
	s_nop 0
	global_load_lds_dwordx4 v198, s[68:69]
	s_add_u32 m0, s76, 0x6000
	s_nop 0
	global_load_lds_dwordx4 v199, s[68:69]
	s_add_u32 m0, s76, 0x8000
	s_nop 0
	global_load_lds_dwordx4 v196, s[70:71]
	s_add_u32 m0, s76, 0xa000
	s_nop 0
	global_load_lds_dwordx4 v197, s[70:71]
	s_sub_u32 s68, s68, 0x80
	s_subb_u32 s69, s69, 0
	s_sub_u32 s70, s70, 0x80
	s_subb_u32 s71, s71, 0
	s_waitcnt lgkmcnt(0)
	s_barrier
	v_mfma_f32_16x16x32_bf16 v[2:5], v[146:149], v[130:133], v[2:5]
	v_mfma_f32_16x16x32_bf16 v[6:9], v[150:153], v[130:133], v[6:9]
	v_mfma_f32_16x16x32_bf16 v[10:13], v[154:157], v[130:133], v[10:13]
	v_mfma_f32_16x16x32_bf16 v[14:17], v[158:161], v[130:133], v[14:17]
	v_mfma_f32_16x16x32_bf16 v[18:21], v[146:149], v[134:137], v[18:21]
	v_mfma_f32_16x16x32_bf16 v[22:25], v[150:153], v[134:137], v[22:25]
	v_mfma_f32_16x16x32_bf16 v[26:29], v[154:157], v[134:137], v[26:29]
	v_mfma_f32_16x16x32_bf16 v[30:33], v[158:161], v[134:137], v[30:33]
	v_mfma_f32_16x16x32_bf16 v[34:37], v[146:149], v[138:141], v[34:37]
	v_mfma_f32_16x16x32_bf16 v[38:41], v[150:153], v[138:141], v[38:41]
	v_mfma_f32_16x16x32_bf16 v[42:45], v[154:157], v[138:141], v[42:45]
	v_mfma_f32_16x16x32_bf16 v[46:49], v[158:161], v[138:141], v[46:49]
	v_mfma_f32_16x16x32_bf16 v[50:53], v[146:149], v[142:145], v[50:53]
	v_mfma_f32_16x16x32_bf16 v[54:57], v[150:153], v[142:145], v[54:57]
	v_mfma_f32_16x16x32_bf16 v[58:61], v[154:157], v[142:145], v[58:61]
	v_mfma_f32_16x16x32_bf16 v[62:65], v[158:161], v[142:145], v[62:65]
	v_mfma_f32_16x16x32_bf16 v[2:5], v[228:231], v[212:215], v[2:5]
	v_mfma_f32_16x16x32_bf16 v[6:9], v[232:235], v[212:215], v[6:9]
	v_mfma_f32_16x16x32_bf16 v[10:13], v[236:239], v[212:215], v[10:13]
	v_mfma_f32_16x16x32_bf16 v[14:17], v[240:243], v[212:215], v[14:17]
	v_mfma_f32_16x16x32_bf16 v[18:21], v[228:231], v[216:219], v[18:21]
	v_mfma_f32_16x16x32_bf16 v[22:25], v[232:235], v[216:219], v[22:25]
	v_mfma_f32_16x16x32_bf16 v[26:29], v[236:239], v[216:219], v[26:29]
	v_mfma_f32_16x16x32_bf16 v[30:33], v[240:243], v[216:219], v[30:33]
	v_mfma_f32_16x16x32_bf16 v[34:37], v[228:231], v[220:223], v[34:37]
	v_mfma_f32_16x16x32_bf16 v[38:41], v[232:235], v[220:223], v[38:41]
	v_mfma_f32_16x16x32_bf16 v[42:45], v[236:239], v[220:223], v[42:45]
	v_mfma_f32_16x16x32_bf16 v[46:49], v[240:243], v[220:223], v[46:49]
	v_mfma_f32_16x16x32_bf16 v[50:53], v[228:231], v[224:227], v[50:53]
	v_mfma_f32_16x16x32_bf16 v[54:57], v[232:235], v[224:227], v[54:57]
	v_mfma_f32_16x16x32_bf16 v[58:61], v[236:239], v[224:227], v[58:61]
	v_mfma_f32_16x16x32_bf16 v[62:65], v[240:243], v[224:227], v[62:65]
	s_waitcnt vmcnt(6)
	s_barrier
	s_mov_b32 s16, 12
.Ldn_kloop1:
	v_add_u32_e32 v204, 0x18000, v200
	v_add_u32_e32 v205, 0x18000, v202
	ds_read_b128 v[130:133], v204 offset:0
	ds_read_b128 v[134:137], v204 offset:2048
	ds_read_b128 v[138:141], v204 offset:4096
	ds_read_b128 v[142:145], v204 offset:6144
	ds_read_b128 v[146:149], v205 offset:0
	ds_read_b128 v[150:153], v205 offset:2048
	ds_read_b128 v[154:157], v205 offset:4096
	ds_read_b128 v[158:161], v205 offset:6144
	v_add_u32_e32 v204, 0x18000, v201
	v_add_u32_e32 v205, 0x18000, v203
	ds_read_b128 v[212:215], v204 offset:0
	ds_read_b128 v[216:219], v204 offset:2048
	ds_read_b128 v[220:223], v204 offset:4096
	ds_read_b128 v[224:227], v204 offset:6144
	ds_read_b128 v[228:231], v205 offset:0
	ds_read_b128 v[232:235], v205 offset:2048
	ds_read_b128 v[236:239], v205 offset:4096
	ds_read_b128 v[240:243], v205 offset:6144
	s_add_u32 m0, s76, 0xc000
	s_nop 0
	global_load_lds_dwordx4 v196, s[68:69]
	s_add_u32 m0, s76, 0xe000
	s_nop 0
	global_load_lds_dwordx4 v197, s[68:69]
	s_add_u32 m0, s76, 0x10000
	s_nop 0
	global_load_lds_dwordx4 v198, s[68:69]
	s_add_u32 m0, s76, 0x12000
	s_nop 0
	global_load_lds_dwordx4 v199, s[68:69]
	s_add_u32 m0, s76, 0x14000
	s_nop 0
	global_load_lds_dwordx4 v196, s[70:71]
	s_add_u32 m0, s76, 0x16000
	s_nop 0
	global_load_lds_dwordx4 v197, s[70:71]
	s_sub_u32 s68, s68, 0x80
	s_subb_u32 s69, s69, 0
	s_sub_u32 s70, s70, 0x80
	s_subb_u32 s71, s71, 0
	s_waitcnt lgkmcnt(0)
	s_barrier
	v_mfma_f32_16x16x32_bf16 v[2:5], v[146:149], v[130:133], v[2:5]
	v_mfma_f32_16x16x32_bf16 v[6:9], v[150:153], v[130:133], v[6:9]
	v_mfma_f32_16x16x32_bf16 v[10:13], v[154:157], v[130:133], v[10:13]
	v_mfma_f32_16x16x32_bf16 v[14:17], v[158:161], v[130:133], v[14:17]
	v_mfma_f32_16x16x32_bf16 v[18:21], v[146:149], v[134:137], v[18:21]
	v_mfma_f32_16x16x32_bf16 v[22:25], v[150:153], v[134:137], v[22:25]
	v_mfma_f32_16x16x32_bf16 v[26:29], v[154:157], v[134:137], v[26:29]
	v_mfma_f32_16x16x32_bf16 v[30:33], v[158:161], v[134:137], v[30:33]
	v_mfma_f32_16x16x32_bf16 v[34:37], v[146:149], v[138:141], v[34:37]
	v_mfma_f32_16x16x32_bf16 v[38:41], v[150:153], v[138:141], v[38:41]
	v_mfma_f32_16x16x32_bf16 v[42:45], v[154:157], v[138:141], v[42:45]
	v_mfma_f32_16x16x32_bf16 v[46:49], v[158:161], v[138:141], v[46:49]
	v_mfma_f32_16x16x32_bf16 v[50:53], v[146:149], v[142:145], v[50:53]
	v_mfma_f32_16x16x32_bf16 v[54:57], v[150:153], v[142:145], v[54:57]
	v_mfma_f32_16x16x32_bf16 v[58:61], v[154:157], v[142:145], v[58:61]
	v_mfma_f32_16x16x32_bf16 v[62:65], v[158:161], v[142:145], v[62:65]
	v_mfma_f32_16x16x32_bf16 v[2:5], v[228:231], v[212:215], v[2:5]
	v_mfma_f32_16x16x32_bf16 v[6:9], v[232:235], v[212:215], v[6:9]
	v_mfma_f32_16x16x32_bf16 v[10:13], v[236:239], v[212:215], v[10:13]
	v_mfma_f32_16x16x32_bf16 v[14:17], v[240:243], v[212:215], v[14:17]
	v_mfma_f32_16x16x32_bf16 v[18:21], v[228:231], v[216:219], v[18:21]
	v_mfma_f32_16x16x32_bf16 v[22:25], v[232:235], v[216:219], v[22:25]
	v_mfma_f32_16x16x32_bf16 v[26:29], v[236:239], v[216:219], v[26:29]
	v_mfma_f32_16x16x32_bf16 v[30:33], v[240:243], v[216:219], v[30:33]
	v_mfma_f32_16x16x32_bf16 v[34:37], v[228:231], v[220:223], v[34:37]
	v_mfma_f32_16x16x32_bf16 v[38:41], v[232:235], v[220:223], v[38:41]
	v_mfma_f32_16x16x32_bf16 v[42:45], v[236:239], v[220:223], v[42:45]
	v_mfma_f32_16x16x32_bf16 v[46:49], v[240:243], v[220:223], v[46:49]
	v_mfma_f32_16x16x32_bf16 v[50:53], v[228:231], v[224:227], v[50:53]
	v_mfma_f32_16x16x32_bf16 v[54:57], v[232:235], v[224:227], v[54:57]
	v_mfma_f32_16x16x32_bf16 v[58:61], v[236:239], v[224:227], v[58:61]
	v_mfma_f32_16x16x32_bf16 v[62:65], v[240:243], v[224:227], v[62:65]
	s_waitcnt vmcnt(6)
	s_barrier
	v_add_u32_e32 v204, 0x0, v200
	v_add_u32_e32 v205, 0x0, v202
	ds_read_b128 v[130:133], v204 offset:0
	ds_read_b128 v[134:137], v204 offset:2048
	ds_read_b128 v[138:141], v204 offset:4096
	ds_read_b128 v[142:145], v204 offset:6144
	ds_read_b128 v[146:149], v205 offset:0
	ds_read_b128 v[150:153], v205 offset:2048
	ds_read_b128 v[154:157], v205 offset:4096
	ds_read_b128 v[158:161], v205 offset:6144
	v_add_u32_e32 v204, 0x0, v201
	v_add_u32_e32 v205, 0x0, v203
	ds_read_b128 v[212:215], v204 offset:0
	ds_read_b128 v[216:219], v204 offset:2048
	ds_read_b128 v[220:223], v204 offset:4096
	ds_read_b128 v[224:227], v204 offset:6144
	ds_read_b128 v[228:231], v205 offset:0
	ds_read_b128 v[232:235], v205 offset:2048
	ds_read_b128 v[236:239], v205 offset:4096
	ds_read_b128 v[240:243], v205 offset:6144
	s_add_u32 m0, s76, 0x18000
	s_nop 0
	global_load_lds_dwordx4 v196, s[68:69]
	s_add_u32 m0, s76, 0x1a000
	s_nop 0
	global_load_lds_dwordx4 v197, s[68:69]
	s_add_u32 m0, s76, 0x1c000
	s_nop 0
	global_load_lds_dwordx4 v198, s[68:69]
	s_add_u32 m0, s76, 0x1e000
	s_nop 0
	global_load_lds_dwordx4 v199, s[68:69]
	s_add_u32 m0, s76, 0x20000
	s_nop 0
	global_load_lds_dwordx4 v196, s[70:71]
	s_add_u32 m0, s76, 0x22000
	s_nop 0
	global_load_lds_dwordx4 v197, s[70:71]
	s_sub_u32 s68, s68, 0x80
	s_subb_u32 s69, s69, 0
	s_sub_u32 s70, s70, 0x80
	s_subb_u32 s71, s71, 0
	s_waitcnt lgkmcnt(0)
	s_barrier
	v_mfma_f32_16x16x32_bf16 v[2:5], v[146:149], v[130:133], v[2:5]
	v_mfma_f32_16x16x32_bf16 v[6:9], v[150:153], v[130:133], v[6:9]
	v_mfma_f32_16x16x32_bf16 v[10:13], v[154:157], v[130:133], v[10:13]
	v_mfma_f32_16x16x32_bf16 v[14:17], v[158:161], v[130:133], v[14:17]
	v_mfma_f32_16x16x32_bf16 v[18:21], v[146:149], v[134:137], v[18:21]
	v_mfma_f32_16x16x32_bf16 v[22:25], v[150:153], v[134:137], v[22:25]
	v_mfma_f32_16x16x32_bf16 v[26:29], v[154:157], v[134:137], v[26:29]
	v_mfma_f32_16x16x32_bf16 v[30:33], v[158:161], v[134:137], v[30:33]
	v_mfma_f32_16x16x32_bf16 v[34:37], v[146:149], v[138:141], v[34:37]
	v_mfma_f32_16x16x32_bf16 v[38:41], v[150:153], v[138:141], v[38:41]
	v_mfma_f32_16x16x32_bf16 v[42:45], v[154:157], v[138:141], v[42:45]
	v_mfma_f32_16x16x32_bf16 v[46:49], v[158:161], v[138:141], v[46:49]
	v_mfma_f32_16x16x32_bf16 v[50:53], v[146:149], v[142:145], v[50:53]
	v_mfma_f32_16x16x32_bf16 v[54:57], v[150:153], v[142:145], v[54:57]
	v_mfma_f32_16x16x32_bf16 v[58:61], v[154:157], v[142:145], v[58:61]
	v_mfma_f32_16x16x32_bf16 v[62:65], v[158:161], v[142:145], v[62:65]
	v_mfma_f32_16x16x32_bf16 v[2:5], v[228:231], v[212:215], v[2:5]
	v_mfma_f32_16x16x32_bf16 v[6:9], v[232:235], v[212:215], v[6:9]
	v_mfma_f32_16x16x32_bf16 v[10:13], v[236:239], v[212:215], v[10:13]
	v_mfma_f32_16x16x32_bf16 v[14:17], v[240:243], v[212:215], v[14:17]
	v_mfma_f32_16x16x32_bf16 v[18:21], v[228:231], v[216:219], v[18:21]
	v_mfma_f32_16x16x32_bf16 v[22:25], v[232:235], v[216:219], v[22:25]
	v_mfma_f32_16x16x32_bf16 v[26:29], v[236:239], v[216:219], v[26:29]
	v_mfma_f32_16x16x32_bf16 v[30:33], v[240:243], v[216:219], v[30:33]
	v_mfma_f32_16x16x32_bf16 v[34:37], v[228:231], v[220:223], v[34:37]
	v_mfma_f32_16x16x32_bf16 v[38:41], v[232:235], v[220:223], v[38:41]
	v_mfma_f32_16x16x32_bf16 v[42:45], v[236:239], v[220:223], v[42:45]
	v_mfma_f32_16x16x32_bf16 v[46:49], v[240:243], v[220:223], v[46:49]
	v_mfma_f32_16x16x32_bf16 v[50:53], v[228:231], v[224:227], v[50:53]
	v_mfma_f32_16x16x32_bf16 v[54:57], v[232:235], v[224:227], v[54:57]
	v_mfma_f32_16x16x32_bf16 v[58:61], v[236:239], v[224:227], v[58:61]
	v_mfma_f32_16x16x32_bf16 v[62:65], v[240:243], v[224:227], v[62:65]
	s_waitcnt vmcnt(6)
	s_barrier
	v_add_u32_e32 v204, 0xc000, v200
	v_add_u32_e32 v205, 0xc000, v202
	ds_read_b128 v[130:133], v204 offset:0
	ds_read_b128 v[134:137], v204 offset:2048
	ds_read_b128 v[138:141], v204 offset:4096
	ds_read_b128 v[142:145], v204 offset:6144
	ds_read_b128 v[146:149], v205 offset:0
	ds_read_b128 v[150:153], v205 offset:2048
	ds_read_b128 v[154:157], v205 offset:4096
	ds_read_b128 v[158:161], v205 offset:6144
	v_add_u32_e32 v204, 0xc000, v201
	v_add_u32_e32 v205, 0xc000, v203
	ds_read_b128 v[212:215], v204 offset:0
	ds_read_b128 v[216:219], v204 offset:2048
	ds_read_b128 v[220:223], v204 offset:4096
	ds_read_b128 v[224:227], v204 offset:6144
	ds_read_b128 v[228:231], v205 offset:0
	ds_read_b128 v[232:235], v205 offset:2048
	ds_read_b128 v[236:239], v205 offset:4096
	ds_read_b128 v[240:243], v205 offset:6144
	s_add_u32 m0, s76, 0x0
	s_nop 0
	global_load_lds_dwordx4 v196, s[68:69]
	s_add_u32 m0, s76, 0x2000
	s_nop 0
	global_load_lds_dwordx4 v197, s[68:69]
	s_add_u32 m0, s76, 0x4000
	s_nop 0
	global_load_lds_dwordx4 v198, s[68:69]
	s_add_u32 m0, s76, 0x6000
	s_nop 0
	global_load_lds_dwordx4 v199, s[68:69]
	s_add_u32 m0, s76, 0x8000
	s_nop 0
	global_load_lds_dwordx4 v196, s[70:71]
	s_add_u32 m0, s76, 0xa000
	s_nop 0
	global_load_lds_dwordx4 v197, s[70:71]
	s_sub_u32 s68, s68, 0x80
	s_subb_u32 s69, s69, 0
	s_sub_u32 s70, s70, 0x80
	s_subb_u32 s71, s71, 0
	s_waitcnt lgkmcnt(0)
	s_barrier
	v_mfma_f32_16x16x32_bf16 v[2:5], v[146:149], v[130:133], v[2:5]
	v_mfma_f32_16x16x32_bf16 v[6:9], v[150:153], v[130:133], v[6:9]
	v_mfma_f32_16x16x32_bf16 v[10:13], v[154:157], v[130:133], v[10:13]
	v_mfma_f32_16x16x32_bf16 v[14:17], v[158:161], v[130:133], v[14:17]
	v_mfma_f32_16x16x32_bf16 v[18:21], v[146:149], v[134:137], v[18:21]
	v_mfma_f32_16x16x32_bf16 v[22:25], v[150:153], v[134:137], v[22:25]
	v_mfma_f32_16x16x32_bf16 v[26:29], v[154:157], v[134:137], v[26:29]
	v_mfma_f32_16x16x32_bf16 v[30:33], v[158:161], v[134:137], v[30:33]
	v_mfma_f32_16x16x32_bf16 v[34:37], v[146:149], v[138:141], v[34:37]
	v_mfma_f32_16x16x32_bf16 v[38:41], v[150:153], v[138:141], v[38:41]
	v_mfma_f32_16x16x32_bf16 v[42:45], v[154:157], v[138:141], v[42:45]
	v_mfma_f32_16x16x32_bf16 v[46:49], v[158:161], v[138:141], v[46:49]
	v_mfma_f32_16x16x32_bf16 v[50:53], v[146:149], v[142:145], v[50:53]
	v_mfma_f32_16x16x32_bf16 v[54:57], v[150:153], v[142:145], v[54:57]
	v_mfma_f32_16x16x32_bf16 v[58:61], v[154:157], v[142:145], v[58:61]
	v_mfma_f32_16x16x32_bf16 v[62:65], v[158:161], v[142:145], v[62:65]
	v_mfma_f32_16x16x32_bf16 v[2:5], v[228:231], v[212:215], v[2:5]
	v_mfma_f32_16x16x32_bf16 v[6:9], v[232:235], v[212:215], v[6:9]
	v_mfma_f32_16x16x32_bf16 v[10:13], v[236:239], v[212:215], v[10:13]
	v_mfma_f32_16x16x32_bf16 v[14:17], v[240:243], v[212:215], v[14:17]
	v_mfma_f32_16x16x32_bf16 v[18:21], v[228:231], v[216:219], v[18:21]
	v_mfma_f32_16x16x32_bf16 v[22:25], v[232:235], v[216:219], v[22:25]
	v_mfma_f32_16x16x32_bf16 v[26:29], v[236:239], v[216:219], v[26:29]
	v_mfma_f32_16x16x32_bf16 v[30:33], v[240:243], v[216:219], v[30:33]
	v_mfma_f32_16x16x32_bf16 v[34:37], v[228:231], v[220:223], v[34:37]
	v_mfma_f32_16x16x32_bf16 v[38:41], v[232:235], v[220:223], v[38:41]
	v_mfma_f32_16x16x32_bf16 v[42:45], v[236:239], v[220:223], v[42:45]
	v_mfma_f32_16x16x32_bf16 v[46:49], v[240:243], v[220:223], v[46:49]
	v_mfma_f32_16x16x32_bf16 v[50:53], v[228:231], v[224:227], v[50:53]
	v_mfma_f32_16x16x32_bf16 v[54:57], v[232:235], v[224:227], v[54:57]
	v_mfma_f32_16x16x32_bf16 v[58:61], v[236:239], v[224:227], v[58:61]
	v_mfma_f32_16x16x32_bf16 v[62:65], v[240:243], v[224:227], v[62:65]
	s_waitcnt vmcnt(6)
	s_barrier
	s_add_i32 s16, s16, -1
	s_cmp_lg_u32 s16, 0
	s_cbranch_scc1 .Ldn_kloop1
	v_add_u32_e32 v204, 0x18000, v200
	v_add_u32_e32 v205, 0x18000, v202
	ds_read_b128 v[130:133], v204 offset:0
	ds_read_b128 v[134:137], v204 offset:2048
	ds_read_b128 v[138:141], v204 offset:4096
	ds_read_b128 v[142:145], v204 offset:6144
	ds_read_b128 v[146:149], v205 offset:0
	ds_read_b128 v[150:153], v205 offset:2048
	ds_read_b128 v[154:157], v205 offset:4096
	ds_read_b128 v[158:161], v205 offset:6144
	v_add_u32_e32 v204, 0x18000, v201
	v_add_u32_e32 v205, 0x18000, v203
	ds_read_b128 v[212:215], v204 offset:0
	ds_read_b128 v[216:219], v204 offset:2048
	ds_read_b128 v[220:223], v204 offset:4096
	ds_read_b128 v[224:227], v204 offset:6144
	ds_read_b128 v[228:231], v205 offset:0
	ds_read_b128 v[232:235], v205 offset:2048
	ds_read_b128 v[236:239], v205 offset:4096
	ds_read_b128 v[240:243], v205 offset:6144
	s_add_u32 m0, s76, 0xc000
	s_nop 0
	global_load_lds_dwordx4 v196, s[68:69]
	s_add_u32 m0, s76, 0xe000
	s_nop 0
	global_load_lds_dwordx4 v197, s[68:69]
	s_add_u32 m0, s76, 0x10000
	s_nop 0
	global_load_lds_dwordx4 v198, s[68:69]
	s_add_u32 m0, s76, 0x12000
	s_nop 0
	global_load_lds_dwordx4 v199, s[68:69]
	s_add_u32 m0, s76, 0x14000
	s_nop 0
	global_load_lds_dwordx4 v196, s[70:71]
	s_add_u32 m0, s76, 0x16000
	s_nop 0
	global_load_lds_dwordx4 v197, s[70:71]
	s_sub_u32 s68, s68, 0x80
	s_subb_u32 s69, s69, 0
	s_sub_u32 s70, s70, 0x80
	s_subb_u32 s71, s71, 0
	s_waitcnt lgkmcnt(0)
	s_barrier
	v_mfma_f32_16x16x32_bf16 v[2:5], v[146:149], v[130:133], v[2:5]
	v_mfma_f32_16x16x32_bf16 v[6:9], v[150:153], v[130:133], v[6:9]
	v_mfma_f32_16x16x32_bf16 v[10:13], v[154:157], v[130:133], v[10:13]
	v_mfma_f32_16x16x32_bf16 v[14:17], v[158:161], v[130:133], v[14:17]
	v_mfma_f32_16x16x32_bf16 v[18:21], v[146:149], v[134:137], v[18:21]
	v_mfma_f32_16x16x32_bf16 v[22:25], v[150:153], v[134:137], v[22:25]
	v_mfma_f32_16x16x32_bf16 v[26:29], v[154:157], v[134:137], v[26:29]
	v_mfma_f32_16x16x32_bf16 v[30:33], v[158:161], v[134:137], v[30:33]
	v_mfma_f32_16x16x32_bf16 v[34:37], v[146:149], v[138:141], v[34:37]
	v_mfma_f32_16x16x32_bf16 v[38:41], v[150:153], v[138:141], v[38:41]
	v_mfma_f32_16x16x32_bf16 v[42:45], v[154:157], v[138:141], v[42:45]
	v_mfma_f32_16x16x32_bf16 v[46:49], v[158:161], v[138:141], v[46:49]
	v_mfma_f32_16x16x32_bf16 v[50:53], v[146:149], v[142:145], v[50:53]
	v_mfma_f32_16x16x32_bf16 v[54:57], v[150:153], v[142:145], v[54:57]
	v_mfma_f32_16x16x32_bf16 v[58:61], v[154:157], v[142:145], v[58:61]
	v_mfma_f32_16x16x32_bf16 v[62:65], v[158:161], v[142:145], v[62:65]
	v_mfma_f32_16x16x32_bf16 v[2:5], v[228:231], v[212:215], v[2:5]
	v_mfma_f32_16x16x32_bf16 v[6:9], v[232:235], v[212:215], v[6:9]
	v_mfma_f32_16x16x32_bf16 v[10:13], v[236:239], v[212:215], v[10:13]
	v_mfma_f32_16x16x32_bf16 v[14:17], v[240:243], v[212:215], v[14:17]
	v_mfma_f32_16x16x32_bf16 v[18:21], v[228:231], v[216:219], v[18:21]
	v_mfma_f32_16x16x32_bf16 v[22:25], v[232:235], v[216:219], v[22:25]
	v_mfma_f32_16x16x32_bf16 v[26:29], v[236:239], v[216:219], v[26:29]
	v_mfma_f32_16x16x32_bf16 v[30:33], v[240:243], v[216:219], v[30:33]
	v_mfma_f32_16x16x32_bf16 v[34:37], v[228:231], v[220:223], v[34:37]
	v_mfma_f32_16x16x32_bf16 v[38:41], v[232:235], v[220:223], v[38:41]
	v_mfma_f32_16x16x32_bf16 v[42:45], v[236:239], v[220:223], v[42:45]
	v_mfma_f32_16x16x32_bf16 v[46:49], v[240:243], v[220:223], v[46:49]
	v_mfma_f32_16x16x32_bf16 v[50:53], v[228:231], v[224:227], v[50:53]
	v_mfma_f32_16x16x32_bf16 v[54:57], v[232:235], v[224:227], v[54:57]
	v_mfma_f32_16x16x32_bf16 v[58:61], v[236:239], v[224:227], v[58:61]
	v_mfma_f32_16x16x32_bf16 v[62:65], v[240:243], v[224:227], v[62:65]
	s_waitcnt vmcnt(6)
	s_barrier
	v_add_u32_e32 v204, 0x0, v200
	v_add_u32_e32 v205, 0x0, v202
	ds_read_b128 v[130:133], v204 offset:0
	ds_read_b128 v[134:137], v204 offset:2048
	ds_read_b128 v[138:141], v204 offset:4096
	ds_read_b128 v[142:145], v204 offset:6144
	ds_read_b128 v[146:149], v205 offset:0
	ds_read_b128 v[150:153], v205 offset:2048
	ds_read_b128 v[154:157], v205 offset:4096
	ds_read_b128 v[158:161], v205 offset:6144
	v_add_u32_e32 v204, 0x0, v201
	v_add_u32_e32 v205, 0x0, v203
	ds_read_b128 v[212:215], v204 offset:0
	ds_read_b128 v[216:219], v204 offset:2048
	ds_read_b128 v[220:223], v204 offset:4096
	ds_read_b128 v[224:227], v204 offset:6144
	ds_read_b128 v[228:231], v205 offset:0
	ds_read_b128 v[232:235], v205 offset:2048
	ds_read_b128 v[236:239], v205 offset:4096
	ds_read_b128 v[240:243], v205 offset:6144
	s_waitcnt lgkmcnt(0)
	s_barrier
	v_mfma_f32_16x16x32_bf16 v[2:5], v[146:149], v[130:133], v[2:5]
	v_mfma_f32_16x16x32_bf16 v[6:9], v[150:153], v[130:133], v[6:9]
	v_mfma_f32_16x16x32_bf16 v[10:13], v[154:157], v[130:133], v[10:13]
	v_mfma_f32_16x16x32_bf16 v[14:17], v[158:161], v[130:133], v[14:17]
	v_mfma_f32_16x16x32_bf16 v[18:21], v[146:149], v[134:137], v[18:21]
	v_mfma_f32_16x16x32_bf16 v[22:25], v[150:153], v[134:137], v[22:25]
	v_mfma_f32_16x16x32_bf16 v[26:29], v[154:157], v[134:137], v[26:29]
	v_mfma_f32_16x16x32_bf16 v[30:33], v[158:161], v[134:137], v[30:33]
	v_mfma_f32_16x16x32_bf16 v[34:37], v[146:149], v[138:141], v[34:37]
	v_mfma_f32_16x16x32_bf16 v[38:41], v[150:153], v[138:141], v[38:41]
	v_mfma_f32_16x16x32_bf16 v[42:45], v[154:157], v[138:141], v[42:45]
	v_mfma_f32_16x16x32_bf16 v[46:49], v[158:161], v[138:141], v[46:49]
	v_mfma_f32_16x16x32_bf16 v[50:53], v[146:149], v[142:145], v[50:53]
	v_mfma_f32_16x16x32_bf16 v[54:57], v[150:153], v[142:145], v[54:57]
	v_mfma_f32_16x16x32_bf16 v[58:61], v[154:157], v[142:145], v[58:61]
	v_mfma_f32_16x16x32_bf16 v[62:65], v[158:161], v[142:145], v[62:65]
	v_mfma_f32_16x16x32_bf16 v[2:5], v[228:231], v[212:215], v[2:5]
	v_mfma_f32_16x16x32_bf16 v[6:9], v[232:235], v[212:215], v[6:9]
	v_mfma_f32_16x16x32_bf16 v[10:13], v[236:239], v[212:215], v[10:13]
	v_mfma_f32_16x16x32_bf16 v[14:17], v[240:243], v[212:215], v[14:17]
	v_mfma_f32_16x16x32_bf16 v[18:21], v[228:231], v[216:219], v[18:21]
	v_mfma_f32_16x16x32_bf16 v[22:25], v[232:235], v[216:219], v[22:25]
	v_mfma_f32_16x16x32_bf16 v[26:29], v[236:239], v[216:219], v[26:29]
	v_mfma_f32_16x16x32_bf16 v[30:33], v[240:243], v[216:219], v[30:33]
	v_mfma_f32_16x16x32_bf16 v[34:37], v[228:231], v[220:223], v[34:37]
	v_mfma_f32_16x16x32_bf16 v[38:41], v[232:235], v[220:223], v[38:41]
	v_mfma_f32_16x16x32_bf16 v[42:45], v[236:239], v[220:223], v[42:45]
	v_mfma_f32_16x16x32_bf16 v[46:49], v[240:243], v[220:223], v[46:49]
	v_mfma_f32_16x16x32_bf16 v[50:53], v[228:231], v[224:227], v[50:53]
	v_mfma_f32_16x16x32_bf16 v[54:57], v[232:235], v[224:227], v[54:57]
	v_mfma_f32_16x16x32_bf16 v[58:61], v[236:239], v[224:227], v[58:61]
	v_mfma_f32_16x16x32_bf16 v[62:65], v[240:243], v[224:227], v[62:65]
	s_waitcnt vmcnt(0)
	s_barrier
	v_add_u32_e32 v204, 0xc000, v200
	v_add_u32_e32 v205, 0xc000, v202
	ds_read_b128 v[130:133], v204 offset:0
	ds_read_b128 v[134:137], v204 offset:2048
	ds_read_b128 v[138:141], v204 offset:4096
	ds_read_b128 v[142:145], v204 offset:6144
	ds_read_b128 v[146:149], v205 offset:0
	ds_read_b128 v[150:153], v205 offset:2048
	ds_read_b128 v[154:157], v205 offset:4096
	ds_read_b128 v[158:161], v205 offset:6144
	v_add_u32_e32 v204, 0xc000, v201
	v_add_u32_e32 v205, 0xc000, v203
	ds_read_b128 v[212:215], v204 offset:0
	ds_read_b128 v[216:219], v204 offset:2048
	ds_read_b128 v[220:223], v204 offset:4096
	ds_read_b128 v[224:227], v204 offset:6144
	ds_read_b128 v[228:231], v205 offset:0
	ds_read_b128 v[232:235], v205 offset:2048
	ds_read_b128 v[236:239], v205 offset:4096
	ds_read_b128 v[240:243], v205 offset:6144
	s_waitcnt lgkmcnt(0)
	s_barrier
	v_mfma_f32_16x16x32_bf16 v[2:5], v[146:149], v[130:133], v[2:5]
	v_mfma_f32_16x16x32_bf16 v[6:9], v[150:153], v[130:133], v[6:9]
	v_mfma_f32_16x16x32_bf16 v[10:13], v[154:157], v[130:133], v[10:13]
	v_mfma_f32_16x16x32_bf16 v[14:17], v[158:161], v[130:133], v[14:17]
	v_mfma_f32_16x16x32_bf16 v[18:21], v[146:149], v[134:137], v[18:21]
	v_mfma_f32_16x16x32_bf16 v[22:25], v[150:153], v[134:137], v[22:25]
	v_mfma_f32_16x16x32_bf16 v[26:29], v[154:157], v[134:137], v[26:29]
	v_mfma_f32_16x16x32_bf16 v[30:33], v[158:161], v[134:137], v[30:33]
	v_mfma_f32_16x16x32_bf16 v[34:37], v[146:149], v[138:141], v[34:37]
	v_mfma_f32_16x16x32_bf16 v[38:41], v[150:153], v[138:141], v[38:41]
	v_mfma_f32_16x16x32_bf16 v[42:45], v[154:157], v[138:141], v[42:45]
	v_mfma_f32_16x16x32_bf16 v[46:49], v[158:161], v[138:141], v[46:49]
	v_mfma_f32_16x16x32_bf16 v[50:53], v[146:149], v[142:145], v[50:53]
	v_mfma_f32_16x16x32_bf16 v[54:57], v[150:153], v[142:145], v[54:57]
	v_mfma_f32_16x16x32_bf16 v[58:61], v[154:157], v[142:145], v[58:61]
	v_mfma_f32_16x16x32_bf16 v[62:65], v[158:161], v[142:145], v[62:65]
	v_mfma_f32_16x16x32_bf16 v[2:5], v[228:231], v[212:215], v[2:5]
	v_mfma_f32_16x16x32_bf16 v[6:9], v[232:235], v[212:215], v[6:9]
	v_mfma_f32_16x16x32_bf16 v[10:13], v[236:239], v[212:215], v[10:13]
	v_mfma_f32_16x16x32_bf16 v[14:17], v[240:243], v[212:215], v[14:17]
	v_mfma_f32_16x16x32_bf16 v[18:21], v[228:231], v[216:219], v[18:21]
	v_mfma_f32_16x16x32_bf16 v[22:25], v[232:235], v[216:219], v[22:25]
	v_mfma_f32_16x16x32_bf16 v[26:29], v[236:239], v[216:219], v[26:29]
	v_mfma_f32_16x16x32_bf16 v[30:33], v[240:243], v[216:219], v[30:33]
	v_mfma_f32_16x16x32_bf16 v[34:37], v[228:231], v[220:223], v[34:37]
	v_mfma_f32_16x16x32_bf16 v[38:41], v[232:235], v[220:223], v[38:41]
	v_mfma_f32_16x16x32_bf16 v[42:45], v[236:239], v[220:223], v[42:45]
	v_mfma_f32_16x16x32_bf16 v[46:49], v[240:243], v[220:223], v[46:49]
	v_mfma_f32_16x16x32_bf16 v[50:53], v[228:231], v[224:227], v[50:53]
	v_mfma_f32_16x16x32_bf16 v[54:57], v[232:235], v[224:227], v[54:57]
	v_mfma_f32_16x16x32_bf16 v[58:61], v[236:239], v[224:227], v[58:61]
	v_mfma_f32_16x16x32_bf16 v[62:65], v[240:243], v[224:227], v[62:65]
	s_barrier
	s_branch .Ldn_join
.Ldn_streamB:
	s_barrier
	v_add_u32_e32 v204, 0x0, v200
	v_add_u32_e32 v205, 0x0, v202
	ds_read_b128 v[130:133], v204 offset:0
	ds_read_b128 v[134:137], v204 offset:2048
	ds_read_b128 v[138:141], v204 offset:4096
	ds_read_b128 v[142:145], v204 offset:6144
	ds_read_b128 v[146:149], v205 offset:0
	ds_read_b128 v[150:153], v205 offset:2048
	ds_read_b128 v[154:157], v205 offset:4096
	ds_read_b128 v[158:161], v205 offset:6144
	v_add_u32_e32 v204, 0x0, v201
	v_add_u32_e32 v205, 0x0, v203
	ds_read_b128 v[212:215], v204 offset:0
	ds_read_b128 v[216:219], v204 offset:2048
	ds_read_b128 v[220:223], v204 offset:4096
	ds_read_b128 v[224:227], v204 offset:6144
	ds_read_b128 v[228:231], v205 offset:0
	ds_read_b128 v[232:235], v205 offset:2048
	ds_read_b128 v[236:239], v205 offset:4096
	ds_read_b128 v[240:243], v205 offset:6144
	s_add_u32 m0, s76, 0x18000
	s_nop 0
	global_load_lds_dwordx4 v196, s[68:69]
	s_add_u32 m0, s76, 0x1a000
	s_nop 0
	global_load_lds_dwordx4 v197, s[68:69]
	s_add_u32 m0, s76, 0x1c000
	s_nop 0
	global_load_lds_dwordx4 v198, s[68:69]
	s_add_u32 m0, s76, 0x1e000
	s_nop 0
	global_load_lds_dwordx4 v199, s[68:69]
	s_add_u32 m0, s76, 0x20000
	s_nop 0
	global_load_lds_dwordx4 v196, s[70:71]
	s_add_u32 m0, s76, 0x22000
	s_nop 0
	global_load_lds_dwordx4 v197, s[70:71]
	s_sub_u32 s68, s68, 0x80
	s_subb_u32 s69, s69, 0
	s_sub_u32 s70, s70, 0x80
	s_subb_u32 s71, s71, 0
	global_load_dwordx4 v[174:177], v190, s[72:73] offset:0
	global_load_dwordx4 v[178:181], v190, s[72:73] offset:64
	global_load_dwordx4 v[182:185], v190, s[72:73] offset:128
	global_load_dwordx4 v[186:189], v190, s[72:73] offset:192
	global_load_dwordx2 v[66:67], v206, s[74:75] offset:0
	global_load_dwordx2 v[70:71], v206, s[74:75] offset:32
	global_load_dwordx2 v[74:75], v206, s[74:75] offset:64
	s_waitcnt vmcnt(13)
	s_waitcnt lgkmcnt(0)
	s_barrier
	v_mfma_f32_16x16x32_bf16 v[2:5], v[146:149], v[130:133], 0
	v_mfma_f32_16x16x32_bf16 v[6:9], v[150:153], v[130:133], 0
	v_mfma_f32_16x16x32_bf16 v[10:13], v[154:157], v[130:133], 0
	v_mfma_f32_16x16x32_bf16 v[14:17], v[158:161], v[130:133], 0
	v_mfma_f32_16x16x32_bf16 v[18:21], v[146:149], v[134:137], 0
	v_mfma_f32_16x16x32_bf16 v[22:25], v[150:153], v[134:137], 0
	v_mfma_f32_16x16x32_bf16 v[26:29], v[154:157], v[134:137], 0
	v_mfma_f32_16x16x32_bf16 v[30:33], v[158:161], v[134:137], 0
	v_mfma_f32_16x16x32_bf16 v[34:37], v[146:149], v[138:141], 0
	v_mfma_f32_16x16x32_bf16 v[38:41], v[150:153], v[138:141], 0
	v_mfma_f32_16x16x32_bf16 v[42:45], v[154:157], v[138:141], 0
	v_mfma_f32_16x16x32_bf16 v[46:49], v[158:161], v[138:141], 0
	v_mfma_f32_16x16x32_bf16 v[50:53], v[146:149], v[142:145], 0
	v_mfma_f32_16x16x32_bf16 v[54:57], v[150:153], v[142:145], 0
	v_mfma_f32_16x16x32_bf16 v[58:61], v[154:157], v[142:145], 0
	v_mfma_f32_16x16x32_bf16 v[62:65], v[158:161], v[142:145], 0
	v_mfma_f32_16x16x32_bf16 v[2:5], v[228:231], v[212:215], v[2:5]
	v_mfma_f32_16x16x32_bf16 v[6:9], v[232:235], v[212:215], v[6:9]
	v_mfma_f32_16x16x32_bf16 v[10:13], v[236:239], v[212:215], v[10:13]
	v_mfma_f32_16x16x32_bf16 v[14:17], v[240:243], v[212:215], v[14:17]
	v_mfma_f32_16x16x32_bf16 v[18:21], v[228:231], v[216:219], v[18:21]
	v_mfma_f32_16x16x32_bf16 v[22:25], v[232:235], v[216:219], v[22:25]
	v_mfma_f32_16x16x32_bf16 v[26:29], v[236:239], v[216:219], v[26:29]
	v_mfma_f32_16x16x32_bf16 v[30:33], v[240:243], v[216:219], v[30:33]
	v_mfma_f32_16x16x32_bf16 v[34:37], v[228:231], v[220:223], v[34:37]
	v_mfma_f32_16x16x32_bf16 v[38:41], v[232:235], v[220:223], v[38:41]
	v_mfma_f32_16x16x32_bf16 v[42:45], v[236:239], v[220:223], v[42:45]
	v_mfma_f32_16x16x32_bf16 v[46:49], v[240:243], v[220:223], v[46:49]
	v_mfma_f32_16x16x32_bf16 v[50:53], v[228:231], v[224:227], v[50:53]
	v_mfma_f32_16x16x32_bf16 v[54:57], v[232:235], v[224:227], v[54:57]
	v_mfma_f32_16x16x32_bf16 v[58:61], v[236:239], v[224:227], v[58:61]
	v_mfma_f32_16x16x32_bf16 v[62:65], v[240:243], v[224:227], v[62:65]
	s_barrier
	v_add_u32_e32 v204, 0xc000, v200
	v_add_u32_e32 v205, 0xc000, v202
	ds_read_b128 v[130:133], v204 offset:0
	ds_read_b128 v[134:137], v204 offset:2048
	ds_read_b128 v[138:141], v204 offset:4096
	ds_read_b128 v[142:145], v204 offset:6144
	ds_read_b128 v[146:149], v205 offset:0
	ds_read_b128 v[150:153], v205 offset:2048
	ds_read_b128 v[154:157], v205 offset:4096
	ds_read_b128 v[158:161], v205 offset:6144
	v_add_u32_e32 v204, 0xc000, v201
	v_add_u32_e32 v205, 0xc000, v203
	ds_read_b128 v[212:215], v204 offset:0
	ds_read_b128 v[216:219], v204 offset:2048
	ds_read_b128 v[220:223], v204 offset:4096
	ds_read_b128 v[224:227], v204 offset:6144
	ds_read_b128 v[228:231], v205 offset:0
	ds_read_b128 v[232:235], v205 offset:2048
	ds_read_b128 v[236:239], v205 offset:4096
	ds_read_b128 v[240:243], v205 offset:6144
	s_add_u32 m0, s76, 0x0
	s_nop 0
	global_load_lds_dwordx4 v196, s[68:69]
	s_add_u32 m0, s76, 0x2000
	s_nop 0
	global_load_lds_dwordx4 v197, s[68:69]
	s_add_u32 m0, s76, 0x4000
	s_nop 0
	global_load_lds_dwordx4 v198, s[68:69]
	s_add_u32 m0, s76, 0x6000
	s_nop 0
	global_load_lds_dwordx4 v199, s[68:69]
	s_add_u32 m0, s76, 0x8000
	s_nop 0
	global_load_lds_dwordx4 v196, s[70:71]
	s_add_u32 m0, s76, 0xa000
	s_nop 0
	global_load_lds_dwordx4 v197, s[70:71]
	s_sub_u32 s68, s68, 0x80
	s_subb_u32 s69, s69, 0
	s_sub_u32 s70, s70, 0x80
	s_subb_u32 s71, s71, 0
	global_load_dwordx2 v[78:79], v206, s[74:75] offset:96
	global_load_dwordx2 v[82:83], v207, s[74:75] offset:0
	global_load_dwordx2 v[86:87], v207, s[74:75] offset:32
	global_load_dwordx2 v[90:91], v207, s[74:75] offset:64
	global_load_dwordx2 v[94:95], v207, s[74:75] offset:96
	global_load_dwordx2 v[98:99], v208, s[74:75] offset:0
	global_load_dwordx2 v[102:103], v208, s[74:75] offset:32
	s_waitcnt vmcnt(20)
	s_waitcnt lgkmcnt(0)
	s_barrier
	v_mfma_f32_16x16x32_bf16 v[2:5], v[146:149], v[130:133], v[2:5]
	v_mfma_f32_16x16x32_bf16 v[6:9], v[150:153], v[130:133], v[6:9]
	v_mfma_f32_16x16x32_bf16 v[10:13], v[154:157], v[130:133], v[10:13]
	v_mfma_f32_16x16x32_bf16 v[14:17], v[158:161], v[130:133], v[14:17]
	v_mfma_f32_16x16x32_bf16 v[18:21], v[146:149], v[134:137], v[18:21]
	v_mfma_f32_16x16x32_bf16 v[22:25], v[150:153], v[134:137], v[22:25]
	v_mfma_f32_16x16x32_bf16 v[26:29], v[154:157], v[134:137], v[26:29]
	v_mfma_f32_16x16x32_bf16 v[30:33], v[158:161], v[134:137], v[30:33]
	v_mfma_f32_16x16x32_bf16 v[34:37], v[146:149], v[138:141], v[34:37]
	v_mfma_f32_16x16x32_bf16 v[38:41], v[150:153], v[138:141], v[38:41]
	v_mfma_f32_16x16x32_bf16 v[42:45], v[154:157], v[138:141], v[42:45]
	v_mfma_f32_16x16x32_bf16 v[46:49], v[158:161], v[138:141], v[46:49]
	v_mfma_f32_16x16x32_bf16 v[50:53], v[146:149], v[142:145], v[50:53]
	v_mfma_f32_16x16x32_bf16 v[54:57], v[150:153], v[142:145], v[54:57]
	v_mfma_f32_16x16x32_bf16 v[58:61], v[154:157], v[142:145], v[58:61]
	v_mfma_f32_16x16x32_bf16 v[62:65], v[158:161], v[142:145], v[62:65]
	v_mfma_f32_16x16x32_bf16 v[2:5], v[228:231], v[212:215], v[2:5]
	v_mfma_f32_16x16x32_bf16 v[6:9], v[232:235], v[212:215], v[6:9]
	v_mfma_f32_16x16x32_bf16 v[10:13], v[236:239], v[212:215], v[10:13]
	v_mfma_f32_16x16x32_bf16 v[14:17], v[240:243], v[212:215], v[14:17]
	v_mfma_f32_16x16x32_bf16 v[18:21], v[228:231], v[216:219], v[18:21]
	v_mfma_f32_16x16x32_bf16 v[22:25], v[232:235], v[216:219], v[22:25]
	v_mfma_f32_16x16x32_bf16 v[26:29], v[236:239], v[216:219], v[26:29]
	v_mfma_f32_16x16x32_bf16 v[30:33], v[240:243], v[216:219], v[30:33]
	v_mfma_f32_16x16x32_bf16 v[34:37], v[228:231], v[220:223], v[34:37]
	v_mfma_f32_16x16x32_bf16 v[38:41], v[232:235], v[220:223], v[38:41]
	v_mfma_f32_16x16x32_bf16 v[42:45], v[236:239], v[220:223], v[42:45]
	v_mfma_f32_16x16x32_bf16 v[46:49], v[240:243], v[220:223], v[46:49]
	v_mfma_f32_16x16x32_bf16 v[50:53], v[228:231], v[224:227], v[50:53]
	v_mfma_f32_16x16x32_bf16 v[54:57], v[232:235], v[224:227], v[54:57]
	v_mfma_f32_16x16x32_bf16 v[58:61], v[236:239], v[224:227], v[58:61]
	v_mfma_f32_16x16x32_bf16 v[62:65], v[240:243], v[224:227], v[62:65]
	s_barrier
	v_add_u32_e32 v204, 0x18000, v200
	v_add_u32_e32 v205, 0x18000, v202
	ds_read_b128 v[130:133], v204 offset:0
	ds_read_b128 v[134:137], v204 offset:2048
	ds_read_b128 v[138:141], v204 offset:4096
	ds_read_b128 v[142:145], v204 offset:6144
	ds_read_b128 v[146:149], v205 offset:0
	ds_read_b128 v[150:153], v205 offset:2048
	ds_read_b128 v[154:157], v205 offset:4096
	ds_read_b128 v[158:161], v205 offset:6144
	v_add_u32_e32 v204, 0x18000, v201
	v_add_u32_e32 v205, 0x18000, v203
	ds_read_b128 v[212:215], v204 offset:0
	ds_read_b128 v[216:219], v204 offset:2048
	ds_read_b128 v[220:223], v204 offset:4096
	ds_read_b128 v[224:227], v204 offset:6144
	ds_read_b128 v[228:231], v205 offset:0
	ds_read_b128 v[232:235], v205 offset:2048
	ds_read_b128 v[236:239], v205 offset:4096
	ds_read_b128 v[240:243], v205 offset:6144
	s_add_u32 m0, s76, 0xc000
	s_nop 0
	global_load_lds_dwordx4 v196, s[68:69]
	s_add_u32 m0, s76, 0xe000
	s_nop 0
	global_load_lds_dwordx4 v197, s[68:69]
	s_add_u32 m0, s76, 0x10000
	s_nop 0
	global_load_lds_dwordx4 v198, s[68:69]
	s_add_u32 m0, s76, 0x12000
	s_nop 0
	global_load_lds_dwordx4 v199, s[68:69]
	s_add_u32 m0, s76, 0x14000
	s_nop 0
	global_load_lds_dwordx4 v196, s[70:71]
	s_add_u32 m0, s76, 0x16000
	s_nop 0
	global_load_lds_dwordx4 v197, s[70:71]
	s_sub_u32 s68, s68, 0x80
	s_subb_u32 s69, s69, 0
	s_sub_u32 s70, s70, 0x80
	s_subb_u32 s71, s71, 0
	global_load_dwordx2 v[106:107], v208, s[74:75] offset:64
	global_load_dwordx2 v[110:111], v208, s[74:75] offset:96
	global_load_dwordx2 v[114:115], v209, s[74:75] offset:0
	global_load_dwordx2 v[118:119], v209, s[74:75] offset:32
	global_load_dwordx2 v[122:123], v209, s[74:75] offset:64
	global_load_dwordx2 v[126:127], v209, s[74:75] offset:96
	s_waitcnt vmcnt(19)
	s_waitcnt lgkmcnt(0)
	s_barrier
	v_mfma_f32_16x16x32_bf16 v[2:5], v[146:149], v[130:133], v[2:5]
	v_mfma_f32_16x16x32_bf16 v[6:9], v[150:153], v[130:133], v[6:9]
	v_mfma_f32_16x16x32_bf16 v[10:13], v[154:157], v[130:133], v[10:13]
	v_mfma_f32_16x16x32_bf16 v[14:17], v[158:161], v[130:133], v[14:17]
	v_mfma_f32_16x16x32_bf16 v[18:21], v[146:149], v[134:137], v[18:21]
	v_mfma_f32_16x16x32_bf16 v[22:25], v[150:153], v[134:137], v[22:25]
	v_mfma_f32_16x16x32_bf16 v[26:29], v[154:157], v[134:137], v[26:29]
	v_mfma_f32_16x16x32_bf16 v[30:33], v[158:161], v[134:137], v[30:33]
	v_mfma_f32_16x16x32_bf16 v[34:37], v[146:149], v[138:141], v[34:37]
	v_mfma_f32_16x16x32_bf16 v[38:41], v[150:153], v[138:141], v[38:41]
	v_mfma_f32_16x16x32_bf16 v[42:45], v[154:157], v[138:141], v[42:45]
	v_mfma_f32_16x16x32_bf16 v[46:49], v[158:161], v[138:141], v[46:49]
	v_mfma_f32_16x16x32_bf16 v[50:53], v[146:149], v[142:145], v[50:53]
	v_mfma_f32_16x16x32_bf16 v[54:57], v[150:153], v[142:145], v[54:57]
	v_mfma_f32_16x16x32_bf16 v[58:61], v[154:157], v[142:145], v[58:61]
	v_mfma_f32_16x16x32_bf16 v[62:65], v[158:161], v[142:145], v[62:65]
	v_mfma_f32_16x16x32_bf16 v[2:5], v[228:231], v[212:215], v[2:5]
	v_mfma_f32_16x16x32_bf16 v[6:9], v[232:235], v[212:215], v[6:9]
	v_mfma_f32_16x16x32_bf16 v[10:13], v[236:239], v[212:215], v[10:13]
	v_mfma_f32_16x16x32_bf16 v[14:17], v[240:243], v[212:215], v[14:17]
	v_mfma_f32_16x16x32_bf16 v[18:21], v[228:231], v[216:219], v[18:21]
	v_mfma_f32_16x16x32_bf16 v[22:25], v[232:235], v[216:219], v[22:25]
	v_mfma_f32_16x16x32_bf16 v[26:29], v[236:239], v[216:219], v[26:29]
	v_mfma_f32_16x16x32_bf16 v[30:33], v[240:243], v[216:219], v[30:33]
	v_mfma_f32_16x16x32_bf16 v[34:37], v[228:231], v[220:223], v[34:37]
	v_mfma_f32_16x16x32_bf16 v[38:41], v[232:235], v[220:223], v[38:41]
	v_mfma_f32_16x16x32_bf16 v[42:45], v[236:239], v[220:223], v[42:45]
	v_mfma_f32_16x16x32_bf16 v[46:49], v[240:243], v[220:223], v[46:49]
	v_mfma_f32_16x16x32_bf16 v[50:53], v[228:231], v[224:227], v[50:53]
	v_mfma_f32_16x16x32_bf16 v[54:57], v[232:235], v[224:227], v[54:57]
	v_mfma_f32_16x16x32_bf16 v[58:61], v[236:239], v[224:227], v[58:61]
	v_mfma_f32_16x16x32_bf16 v[62:65], v[240:243], v[224:227], v[62:65]
	s_barrier
	v_add_u32_e32 v204, 0x0, v200
	v_add_u32_e32 v205, 0x0, v202
	ds_read_b128 v[130:133], v204 offset:0
	ds_read_b128 v[134:137], v204 offset:2048
	ds_read_b128 v[138:141], v204 offset:4096
	ds_read_b128 v[142:145], v204 offset:6144
	ds_read_b128 v[146:149], v205 offset:0
	ds_read_b128 v[150:153], v205 offset:2048
	ds_read_b128 v[154:157], v205 offset:4096
	ds_read_b128 v[158:161], v205 offset:6144
	v_add_u32_e32 v204, 0x0, v201
	v_add_u32_e32 v205, 0x0, v203
	ds_read_b128 v[212:215], v204 offset:0
	ds_read_b128 v[216:219], v204 offset:2048
	ds_read_b128 v[220:223], v204 offset:4096
	ds_read_b128 v[224:227], v204 offset:6144
	ds_read_b128 v[228:231], v205 offset:0
	ds_read_b128 v[232:235], v205 offset:2048
	ds_read_b128 v[236:239], v205 offset:4096
	ds_read_b128 v[240:243], v205 offset:6144
	s_add_u32 m0, s76, 0x18000
	s_nop 0
	global_load_lds_dwordx4 v196, s[68:69]
	s_add_u32 m0, s76, 0x1a000
	s_nop 0
	global_load_lds_dwordx4 v197, s[68:69]
	s_add_u32 m0, s76, 0x1c000
	s_nop 0
	global_load_lds_dwordx4 v198, s[68:69]
	s_add_u32 m0, s76, 0x1e000
	s_nop 0
	global_load_lds_dwordx4 v199, s[68:69]
	s_add_u32 m0, s76, 0x20000
	s_nop 0
	global_load_lds_dwordx4 v196, s[70:71]
	s_add_u32 m0, s76, 0x22000
	s_nop 0
	global_load_lds_dwordx4 v197, s[70:71]
	s_sub_u32 s68, s68, 0x80
	s_subb_u32 s69, s69, 0
	s_sub_u32 s70, s70, 0x80
	s_subb_u32 s71, s71, 0
	s_waitcnt vmcnt(12)
	s_waitcnt lgkmcnt(0)
	s_barrier
	v_mfma_f32_16x16x32_bf16 v[2:5], v[146:149], v[130:133], v[2:5]
	v_mfma_f32_16x16x32_bf16 v[6:9], v[150:153], v[130:133], v[6:9]
	v_mfma_f32_16x16x32_bf16 v[10:13], v[154:157], v[130:133], v[10:13]
	v_mfma_f32_16x16x32_bf16 v[14:17], v[158:161], v[130:133], v[14:17]
	v_mfma_f32_16x16x32_bf16 v[18:21], v[146:149], v[134:137], v[18:21]
	v_mfma_f32_16x16x32_bf16 v[22:25], v[150:153], v[134:137], v[22:25]
	v_mfma_f32_16x16x32_bf16 v[26:29], v[154:157], v[134:137], v[26:29]
	v_mfma_f32_16x16x32_bf16 v[30:33], v[158:161], v[134:137], v[30:33]
	v_mfma_f32_16x16x32_bf16 v[34:37], v[146:149], v[138:141], v[34:37]
	v_mfma_f32_16x16x32_bf16 v[38:41], v[150:153], v[138:141], v[38:41]
	v_mfma_f32_16x16x32_bf16 v[42:45], v[154:157], v[138:141], v[42:45]
	v_mfma_f32_16x16x32_bf16 v[46:49], v[158:161], v[138:141], v[46:49]
	v_mfma_f32_16x16x32_bf16 v[50:53], v[146:149], v[142:145], v[50:53]
	v_mfma_f32_16x16x32_bf16 v[54:57], v[150:153], v[142:145], v[54:57]
	v_mfma_f32_16x16x32_bf16 v[58:61], v[154:157], v[142:145], v[58:61]
	v_mfma_f32_16x16x32_bf16 v[62:65], v[158:161], v[142:145], v[62:65]
	v_mfma_f32_16x16x32_bf16 v[2:5], v[228:231], v[212:215], v[2:5]
	v_mfma_f32_16x16x32_bf16 v[6:9], v[232:235], v[212:215], v[6:9]
	v_mfma_f32_16x16x32_bf16 v[10:13], v[236:239], v[212:215], v[10:13]
	v_mfma_f32_16x16x32_bf16 v[14:17], v[240:243], v[212:215], v[14:17]
	v_mfma_f32_16x16x32_bf16 v[18:21], v[228:231], v[216:219], v[18:21]
	v_mfma_f32_16x16x32_bf16 v[22:25], v[232:235], v[216:219], v[22:25]
	v_mfma_f32_16x16x32_bf16 v[26:29], v[236:239], v[216:219], v[26:29]
	v_mfma_f32_16x16x32_bf16 v[30:33], v[240:243], v[216:219], v[30:33]
	v_mfma_f32_16x16x32_bf16 v[34:37], v[228:231], v[220:223], v[34:37]
	v_mfma_f32_16x16x32_bf16 v[38:41], v[232:235], v[220:223], v[38:41]
	v_mfma_f32_16x16x32_bf16 v[42:45], v[236:239], v[220:223], v[42:45]
	v_mfma_f32_16x16x32_bf16 v[46:49], v[240:243], v[220:223], v[46:49]
	v_mfma_f32_16x16x32_bf16 v[50:53], v[228:231], v[224:227], v[50:53]
	v_mfma_f32_16x16x32_bf16 v[54:57], v[232:235], v[224:227], v[54:57]
	v_mfma_f32_16x16x32_bf16 v[58:61], v[236:239], v[224:227], v[58:61]
	v_mfma_f32_16x16x32_bf16 v[62:65], v[240:243], v[224:227], v[62:65]
	s_barrier
	v_add_u32_e32 v204, 0xc000, v200
	v_add_u32_e32 v205, 0xc000, v202
	ds_read_b128 v[130:133], v204 offset:0
	ds_read_b128 v[134:137], v204 offset:2048
	ds_read_b128 v[138:141], v204 offset:4096
	ds_read_b128 v[142:145], v204 offset:6144
	ds_read_b128 v[146:149], v205 offset:0
	ds_read_b128 v[150:153], v205 offset:2048
	ds_read_b128 v[154:157], v205 offset:4096
	ds_read_b128 v[158:161], v205 offset:6144
	v_add_u32_e32 v204, 0xc000, v201
	v_add_u32_e32 v205, 0xc000, v203
	ds_read_b128 v[212:215], v204 offset:0
	ds_read_b128 v[216:219], v204 offset:2048
	ds_read_b128 v[220:223], v204 offset:4096
	ds_read_b128 v[224:227], v204 offset:6144
	ds_read_b128 v[228:231], v205 offset:0
	ds_read_b128 v[232:235], v205 offset:2048
	ds_read_b128 v[236:239], v205 offset:4096
	ds_read_b128 v[240:243], v205 offset:6144
	s_add_u32 m0, s76, 0x0
	s_nop 0
	global_load_lds_dwordx4 v196, s[68:69]
	s_add_u32 m0, s76, 0x2000
	s_nop 0
	global_load_lds_dwordx4 v197, s[68:69]
	s_add_u32 m0, s76, 0x4000
	s_nop 0
	global_load_lds_dwordx4 v198, s[68:69]
	s_add_u32 m0, s76, 0x6000
	s_nop 0
	global_load_lds_dwordx4 v199, s[68:69]
	s_add_u32 m0, s76, 0x8000
	s_nop 0
	global_load_lds_dwordx4 v196, s[70:71]
	s_add_u32 m0, s76, 0xa000
	s_nop 0
	global_load_lds_dwordx4 v197, s[70:71]
	s_sub_u32 s68, s68, 0x80
	s_subb_u32 s69, s69, 0
	s_sub_u32 s70, s70, 0x80
	s_subb_u32 s71, s71, 0
	s_waitcnt vmcnt(6)
	s_waitcnt lgkmcnt(0)
	s_barrier
	v_mfma_f32_16x16x32_bf16 v[2:5], v[146:149], v[130:133], v[2:5]
	v_mfma_f32_16x16x32_bf16 v[6:9], v[150:153], v[130:133], v[6:9]
	v_mfma_f32_16x16x32_bf16 v[10:13], v[154:157], v[130:133], v[10:13]
	v_mfma_f32_16x16x32_bf16 v[14:17], v[158:161], v[130:133], v[14:17]
	v_mfma_f32_16x16x32_bf16 v[18:21], v[146:149], v[134:137], v[18:21]
	v_mfma_f32_16x16x32_bf16 v[22:25], v[150:153], v[134:137], v[22:25]
	v_mfma_f32_16x16x32_bf16 v[26:29], v[154:157], v[134:137], v[26:29]
	v_mfma_f32_16x16x32_bf16 v[30:33], v[158:161], v[134:137], v[30:33]
	v_mfma_f32_16x16x32_bf16 v[34:37], v[146:149], v[138:141], v[34:37]
	v_mfma_f32_16x16x32_bf16 v[38:41], v[150:153], v[138:141], v[38:41]
	v_mfma_f32_16x16x32_bf16 v[42:45], v[154:157], v[138:141], v[42:45]
	v_mfma_f32_16x16x32_bf16 v[46:49], v[158:161], v[138:141], v[46:49]
	v_mfma_f32_16x16x32_bf16 v[50:53], v[146:149], v[142:145], v[50:53]
	v_mfma_f32_16x16x32_bf16 v[54:57], v[150:153], v[142:145], v[54:57]
	v_mfma_f32_16x16x32_bf16 v[58:61], v[154:157], v[142:145], v[58:61]
	v_mfma_f32_16x16x32_bf16 v[62:65], v[158:161], v[142:145], v[62:65]
	v_mfma_f32_16x16x32_bf16 v[2:5], v[228:231], v[212:215], v[2:5]
	v_mfma_f32_16x16x32_bf16 v[6:9], v[232:235], v[212:215], v[6:9]
	v_mfma_f32_16x16x32_bf16 v[10:13], v[236:239], v[212:215], v[10:13]
	v_mfma_f32_16x16x32_bf16 v[14:17], v[240:243], v[212:215], v[14:17]
	v_mfma_f32_16x16x32_bf16 v[18:21], v[228:231], v[216:219], v[18:21]
	v_mfma_f32_16x16x32_bf16 v[22:25], v[232:235], v[216:219], v[22:25]
	v_mfma_f32_16x16x32_bf16 v[26:29], v[236:239], v[216:219], v[26:29]
	v_mfma_f32_16x16x32_bf16 v[30:33], v[240:243], v[216:219], v[30:33]
	v_mfma_f32_16x16x32_bf16 v[34:37], v[228:231], v[220:223], v[34:37]
	v_mfma_f32_16x16x32_bf16 v[38:41], v[232:235], v[220:223], v[38:41]
	v_mfma_f32_16x16x32_bf16 v[42:45], v[236:239], v[220:223], v[42:45]
	v_mfma_f32_16x16x32_bf16 v[46:49], v[240:243], v[220:223], v[46:49]
	v_mfma_f32_16x16x32_bf16 v[50:53], v[228:231], v[224:227], v[50:53]
	v_mfma_f32_16x16x32_bf16 v[54:57], v[232:235], v[224:227], v[54:57]
	v_mfma_f32_16x16x32_bf16 v[58:61], v[236:239], v[224:227], v[58:61]
	v_mfma_f32_16x16x32_bf16 v[62:65], v[240:243], v[224:227], v[62:65]
	s_barrier
	s_mov_b32 s16, 12
.Ldn_kloop2:
	v_add_u32_e32 v204, 0x18000, v200
	v_add_u32_e32 v205, 0x18000, v202
	ds_read_b128 v[130:133], v204 offset:0
	ds_read_b128 v[134:137], v204 offset:2048
	ds_read_b128 v[138:141], v204 offset:4096
	ds_read_b128 v[142:145], v204 offset:6144
	ds_read_b128 v[146:149], v205 offset:0
	ds_read_b128 v[150:153], v205 offset:2048
	ds_read_b128 v[154:157], v205 offset:4096
	ds_read_b128 v[158:161], v205 offset:6144
	v_add_u32_e32 v204, 0x18000, v201
	v_add_u32_e32 v205, 0x18000, v203
	ds_read_b128 v[212:215], v204 offset:0
	ds_read_b128 v[216:219], v204 offset:2048
	ds_read_b128 v[220:223], v204 offset:4096
	ds_read_b128 v[224:227], v204 offset:6144
	ds_read_b128 v[228:231], v205 offset:0
	ds_read_b128 v[232:235], v205 offset:2048
	ds_read_b128 v[236:239], v205 offset:4096
	ds_read_b128 v[240:243], v205 offset:6144
	s_add_u32 m0, s76, 0xc000
	s_nop 0
	global_load_lds_dwordx4 v196, s[68:69]
	s_add_u32 m0, s76, 0xe000
	s_nop 0
	global_load_lds_dwordx4 v197, s[68:69]
	s_add_u32 m0, s76, 0x10000
	s_nop 0
	global_load_lds_dwordx4 v198, s[68:69]
	s_add_u32 m0, s76, 0x12000
	s_nop 0
	global_load_lds_dwordx4 v199, s[68:69]
	s_add_u32 m0, s76, 0x14000
	s_nop 0
	global_load_lds_dwordx4 v196, s[70:71]
	s_add_u32 m0, s76, 0x16000
	s_nop 0
	global_load_lds_dwordx4 v197, s[70:71]
	s_sub_u32 s68, s68, 0x80
	s_subb_u32 s69, s69, 0
	s_sub_u32 s70, s70, 0x80
	s_subb_u32 s71, s71, 0
	s_waitcnt vmcnt(6)
	s_waitcnt lgkmcnt(0)
	s_barrier
	v_mfma_f32_16x16x32_bf16 v[2:5], v[146:149], v[130:133], v[2:5]
	v_mfma_f32_16x16x32_bf16 v[6:9], v[150:153], v[130:133], v[6:9]
	v_mfma_f32_16x16x32_bf16 v[10:13], v[154:157], v[130:133], v[10:13]
	v_mfma_f32_16x16x32_bf16 v[14:17], v[158:161], v[130:133], v[14:17]
	v_mfma_f32_16x16x32_bf16 v[18:21], v[146:149], v[134:137], v[18:21]
	v_mfma_f32_16x16x32_bf16 v[22:25], v[150:153], v[134:137], v[22:25]
	v_mfma_f32_16x16x32_bf16 v[26:29], v[154:157], v[134:137], v[26:29]
	v_mfma_f32_16x16x32_bf16 v[30:33], v[158:161], v[134:137], v[30:33]
	v_mfma_f32_16x16x32_bf16 v[34:37], v[146:149], v[138:141], v[34:37]
	v_mfma_f32_16x16x32_bf16 v[38:41], v[150:153], v[138:141], v[38:41]
	v_mfma_f32_16x16x32_bf16 v[42:45], v[154:157], v[138:141], v[42:45]
	v_mfma_f32_16x16x32_bf16 v[46:49], v[158:161], v[138:141], v[46:49]
	v_mfma_f32_16x16x32_bf16 v[50:53], v[146:149], v[142:145], v[50:53]
	v_mfma_f32_16x16x32_bf16 v[54:57], v[150:153], v[142:145], v[54:57]
	v_mfma_f32_16x16x32_bf16 v[58:61], v[154:157], v[142:145], v[58:61]
	v_mfma_f32_16x16x32_bf16 v[62:65], v[158:161], v[142:145], v[62:65]
	v_mfma_f32_16x16x32_bf16 v[2:5], v[228:231], v[212:215], v[2:5]
	v_mfma_f32_16x16x32_bf16 v[6:9], v[232:235], v[212:215], v[6:9]
	v_mfma_f32_16x16x32_bf16 v[10:13], v[236:239], v[212:215], v[10:13]
	v_mfma_f32_16x16x32_bf16 v[14:17], v[240:243], v[212:215], v[14:17]
	v_mfma_f32_16x16x32_bf16 v[18:21], v[228:231], v[216:219], v[18:21]
	v_mfma_f32_16x16x32_bf16 v[22:25], v[232:235], v[216:219], v[22:25]
	v_mfma_f32_16x16x32_bf16 v[26:29], v[236:239], v[216:219], v[26:29]
	v_mfma_f32_16x16x32_bf16 v[30:33], v[240:243], v[216:219], v[30:33]
	v_mfma_f32_16x16x32_bf16 v[34:37], v[228:231], v[220:223], v[34:37]
	v_mfma_f32_16x16x32_bf16 v[38:41], v[232:235], v[220:223], v[38:41]
	v_mfma_f32_16x16x32_bf16 v[42:45], v[236:239], v[220:223], v[42:45]
	v_mfma_f32_16x16x32_bf16 v[46:49], v[240:243], v[220:223], v[46:49]
	v_mfma_f32_16x16x32_bf16 v[50:53], v[228:231], v[224:227], v[50:53]
	v_mfma_f32_16x16x32_bf16 v[54:57], v[232:235], v[224:227], v[54:57]
	v_mfma_f32_16x16x32_bf16 v[58:61], v[236:239], v[224:227], v[58:61]
	v_mfma_f32_16x16x32_bf16 v[62:65], v[240:243], v[224:227], v[62:65]
	s_barrier
	v_add_u32_e32 v204, 0x0, v200
	v_add_u32_e32 v205, 0x0, v202
	ds_read_b128 v[130:133], v204 offset:0
	ds_read_b128 v[134:137], v204 offset:2048
	ds_read_b128 v[138:141], v204 offset:4096
	ds_read_b128 v[142:145], v204 offset:6144
	ds_read_b128 v[146:149], v205 offset:0
	ds_read_b128 v[150:153], v205 offset:2048
	ds_read_b128 v[154:157], v205 offset:4096
	ds_read_b128 v[158:161], v205 offset:6144
	v_add_u32_e32 v204, 0x0, v201
	v_add_u32_e32 v205, 0x0, v203
	ds_read_b128 v[212:215], v204 offset:0
	ds_read_b128 v[216:219], v204 offset:2048
	ds_read_b128 v[220:223], v204 offset:4096
	ds_read_b128 v[224:227], v204 offset:6144
	ds_read_b128 v[228:231], v205 offset:0
	ds_read_b128 v[232:235], v205 offset:2048
	ds_read_b128 v[236:239], v205 offset:4096
	ds_read_b128 v[240:243], v205 offset:6144
	s_add_u32 m0, s76, 0x18000
	s_nop 0
	global_load_lds_dwordx4 v196, s[68:69]
	s_add_u32 m0, s76, 0x1a000
	s_nop 0
	global_load_lds_dwordx4 v197, s[68:69]
	s_add_u32 m0, s76, 0x1c000
	s_nop 0
	global_load_lds_dwordx4 v198, s[68:69]
	s_add_u32 m0, s76, 0x1e000
	s_nop 0
	global_load_lds_dwordx4 v199, s[68:69]
	s_add_u32 m0, s76, 0x20000
	s_nop 0
	global_load_lds_dwordx4 v196, s[70:71]
	s_add_u32 m0, s76, 0x22000
	s_nop 0
	global_load_lds_dwordx4 v197, s[70:71]
	s_sub_u32 s68, s68, 0x80
	s_subb_u32 s69, s69, 0
	s_sub_u32 s70, s70, 0x80
	s_subb_u32 s71, s71, 0
	s_waitcnt vmcnt(6)
	s_waitcnt lgkmcnt(0)
	s_barrier
	v_mfma_f32_16x16x32_bf16 v[2:5], v[146:149], v[130:133], v[2:5]
	v_mfma_f32_16x16x32_bf16 v[6:9], v[150:153], v[130:133], v[6:9]
	v_mfma_f32_16x16x32_bf16 v[10:13], v[154:157], v[130:133], v[10:13]
	v_mfma_f32_16x16x32_bf16 v[14:17], v[158:161], v[130:133], v[14:17]
	v_mfma_f32_16x16x32_bf16 v[18:21], v[146:149], v[134:137], v[18:21]
	v_mfma_f32_16x16x32_bf16 v[22:25], v[150:153], v[134:137], v[22:25]
	v_mfma_f32_16x16x32_bf16 v[26:29], v[154:157], v[134:137], v[26:29]
	v_mfma_f32_16x16x32_bf16 v[30:33], v[158:161], v[134:137], v[30:33]
	v_mfma_f32_16x16x32_bf16 v[34:37], v[146:149], v[138:141], v[34:37]
	v_mfma_f32_16x16x32_bf16 v[38:41], v[150:153], v[138:141], v[38:41]
	v_mfma_f32_16x16x32_bf16 v[42:45], v[154:157], v[138:141], v[42:45]
	v_mfma_f32_16x16x32_bf16 v[46:49], v[158:161], v[138:141], v[46:49]
	v_mfma_f32_16x16x32_bf16 v[50:53], v[146:149], v[142:145], v[50:53]
	v_mfma_f32_16x16x32_bf16 v[54:57], v[150:153], v[142:145], v[54:57]
	v_mfma_f32_16x16x32_bf16 v[58:61], v[154:157], v[142:145], v[58:61]
	v_mfma_f32_16x16x32_bf16 v[62:65], v[158:161], v[142:145], v[62:65]
	v_mfma_f32_16x16x32_bf16 v[2:5], v[228:231], v[212:215], v[2:5]
	v_mfma_f32_16x16x32_bf16 v[6:9], v[232:235], v[212:215], v[6:9]
	v_mfma_f32_16x16x32_bf16 v[10:13], v[236:239], v[212:215], v[10:13]
	v_mfma_f32_16x16x32_bf16 v[14:17], v[240:243], v[212:215], v[14:17]
	v_mfma_f32_16x16x32_bf16 v[18:21], v[228:231], v[216:219], v[18:21]
	v_mfma_f32_16x16x32_bf16 v[22:25], v[232:235], v[216:219], v[22:25]
	v_mfma_f32_16x16x32_bf16 v[26:29], v[236:239], v[216:219], v[26:29]
	v_mfma_f32_16x16x32_bf16 v[30:33], v[240:243], v[216:219], v[30:33]
	v_mfma_f32_16x16x32_bf16 v[34:37], v[228:231], v[220:223], v[34:37]
	v_mfma_f32_16x16x32_bf16 v[38:41], v[232:235], v[220:223], v[38:41]
	v_mfma_f32_16x16x32_bf16 v[42:45], v[236:239], v[220:223], v[42:45]
	v_mfma_f32_16x16x32_bf16 v[46:49], v[240:243], v[220:223], v[46:49]
	v_mfma_f32_16x16x32_bf16 v[50:53], v[228:231], v[224:227], v[50:53]
	v_mfma_f32_16x16x32_bf16 v[54:57], v[232:235], v[224:227], v[54:57]
	v_mfma_f32_16x16x32_bf16 v[58:61], v[236:239], v[224:227], v[58:61]
	v_mfma_f32_16x16x32_bf16 v[62:65], v[240:243], v[224:227], v[62:65]
	s_barrier
	v_add_u32_e32 v204, 0xc000, v200
	v_add_u32_e32 v205, 0xc000, v202
	ds_read_b128 v[130:133], v204 offset:0
	ds_read_b128 v[134:137], v204 offset:2048
	ds_read_b128 v[138:141], v204 offset:4096
	ds_read_b128 v[142:145], v204 offset:6144
	ds_read_b128 v[146:149], v205 offset:0
	ds_read_b128 v[150:153], v205 offset:2048
	ds_read_b128 v[154:157], v205 offset:4096
	ds_read_b128 v[158:161], v205 offset:6144
	v_add_u32_e32 v204, 0xc000, v201
	v_add_u32_e32 v205, 0xc000, v203
	ds_read_b128 v[212:215], v204 offset:0
	ds_read_b128 v[216:219], v204 offset:2048
	ds_read_b128 v[220:223], v204 offset:4096
	ds_read_b128 v[224:227], v204 offset:6144
	ds_read_b128 v[228:231], v205 offset:0
	ds_read_b128 v[232:235], v205 offset:2048
	ds_read_b128 v[236:239], v205 offset:4096
	ds_read_b128 v[240:243], v205 offset:6144
	s_add_u32 m0, s76, 0x0
	s_nop 0
	global_load_lds_dwordx4 v196, s[68:69]
	s_add_u32 m0, s76, 0x2000
	s_nop 0
	global_load_lds_dwordx4 v197, s[68:69]
	s_add_u32 m0, s76, 0x4000
	s_nop 0
	global_load_lds_dwordx4 v198, s[68:69]
	s_add_u32 m0, s76, 0x6000
	s_nop 0
	global_load_lds_dwordx4 v199, s[68:69]
	s_add_u32 m0, s76, 0x8000
	s_nop 0
	global_load_lds_dwordx4 v196, s[70:71]
	s_add_u32 m0, s76, 0xa000
	s_nop 0
	global_load_lds_dwordx4 v197, s[70:71]
	s_sub_u32 s68, s68, 0x80
	s_subb_u32 s69, s69, 0
	s_sub_u32 s70, s70, 0x80
	s_subb_u32 s71, s71, 0
	s_waitcnt vmcnt(6)
	s_waitcnt lgkmcnt(0)
	s_barrier
	v_mfma_f32_16x16x32_bf16 v[2:5], v[146:149], v[130:133], v[2:5]
	v_mfma_f32_16x16x32_bf16 v[6:9], v[150:153], v[130:133], v[6:9]
	v_mfma_f32_16x16x32_bf16 v[10:13], v[154:157], v[130:133], v[10:13]
	v_mfma_f32_16x16x32_bf16 v[14:17], v[158:161], v[130:133], v[14:17]
	v_mfma_f32_16x16x32_bf16 v[18:21], v[146:149], v[134:137], v[18:21]
	v_mfma_f32_16x16x32_bf16 v[22:25], v[150:153], v[134:137], v[22:25]
	v_mfma_f32_16x16x32_bf16 v[26:29], v[154:157], v[134:137], v[26:29]
	v_mfma_f32_16x16x32_bf16 v[30:33], v[158:161], v[134:137], v[30:33]
	v_mfma_f32_16x16x32_bf16 v[34:37], v[146:149], v[138:141], v[34:37]
	v_mfma_f32_16x16x32_bf16 v[38:41], v[150:153], v[138:141], v[38:41]
	v_mfma_f32_16x16x32_bf16 v[42:45], v[154:157], v[138:141], v[42:45]
	v_mfma_f32_16x16x32_bf16 v[46:49], v[158:161], v[138:141], v[46:49]
	v_mfma_f32_16x16x32_bf16 v[50:53], v[146:149], v[142:145], v[50:53]
	v_mfma_f32_16x16x32_bf16 v[54:57], v[150:153], v[142:145], v[54:57]
	v_mfma_f32_16x16x32_bf16 v[58:61], v[154:157], v[142:145], v[58:61]
	v_mfma_f32_16x16x32_bf16 v[62:65], v[158:161], v[142:145], v[62:65]
	v_mfma_f32_16x16x32_bf16 v[2:5], v[228:231], v[212:215], v[2:5]
	v_mfma_f32_16x16x32_bf16 v[6:9], v[232:235], v[212:215], v[6:9]
	v_mfma_f32_16x16x32_bf16 v[10:13], v[236:239], v[212:215], v[10:13]
	v_mfma_f32_16x16x32_bf16 v[14:17], v[240:243], v[212:215], v[14:17]
	v_mfma_f32_16x16x32_bf16 v[18:21], v[228:231], v[216:219], v[18:21]
	v_mfma_f32_16x16x32_bf16 v[22:25], v[232:235], v[216:219], v[22:25]
	v_mfma_f32_16x16x32_bf16 v[26:29], v[236:239], v[216:219], v[26:29]
	v_mfma_f32_16x16x32_bf16 v[30:33], v[240:243], v[216:219], v[30:33]
	v_mfma_f32_16x16x32_bf16 v[34:37], v[228:231], v[220:223], v[34:37]
	v_mfma_f32_16x16x32_bf16 v[38:41], v[232:235], v[220:223], v[38:41]
	v_mfma_f32_16x16x32_bf16 v[42:45], v[236:239], v[220:223], v[42:45]
	v_mfma_f32_16x16x32_bf16 v[46:49], v[240:243], v[220:223], v[46:49]
	v_mfma_f32_16x16x32_bf16 v[50:53], v[228:231], v[224:227], v[50:53]
	v_mfma_f32_16x16x32_bf16 v[54:57], v[232:235], v[224:227], v[54:57]
	v_mfma_f32_16x16x32_bf16 v[58:61], v[236:239], v[224:227], v[58:61]
	v_mfma_f32_16x16x32_bf16 v[62:65], v[240:243], v[224:227], v[62:65]
	s_barrier
	s_add_i32 s16, s16, -1
	s_cmp_lg_u32 s16, 0
	s_cbranch_scc1 .Ldn_kloop2
	v_add_u32_e32 v204, 0x18000, v200
	v_add_u32_e32 v205, 0x18000, v202
	ds_read_b128 v[130:133], v204 offset:0
	ds_read_b128 v[134:137], v204 offset:2048
	ds_read_b128 v[138:141], v204 offset:4096
	ds_read_b128 v[142:145], v204 offset:6144
	ds_read_b128 v[146:149], v205 offset:0
	ds_read_b128 v[150:153], v205 offset:2048
	ds_read_b128 v[154:157], v205 offset:4096
	ds_read_b128 v[158:161], v205 offset:6144
	v_add_u32_e32 v204, 0x18000, v201
	v_add_u32_e32 v205, 0x18000, v203
	ds_read_b128 v[212:215], v204 offset:0
	ds_read_b128 v[216:219], v204 offset:2048
	ds_read_b128 v[220:223], v204 offset:4096
	ds_read_b128 v[224:227], v204 offset:6144
	ds_read_b128 v[228:231], v205 offset:0
	ds_read_b128 v[232:235], v205 offset:2048
	ds_read_b128 v[236:239], v205 offset:4096
	ds_read_b128 v[240:243], v205 offset:6144
	s_add_u32 m0, s76, 0xc000
	s_nop 0
	global_load_lds_dwordx4 v196, s[68:69]
	s_add_u32 m0, s76, 0xe000
	s_nop 0
	global_load_lds_dwordx4 v197, s[68:69]
	s_add_u32 m0, s76, 0x10000
	s_nop 0
	global_load_lds_dwordx4 v198, s[68:69]
	s_add_u32 m0, s76, 0x12000
	s_nop 0
	global_load_lds_dwordx4 v199, s[68:69]
	s_add_u32 m0, s76, 0x14000
	s_nop 0
	global_load_lds_dwordx4 v196, s[70:71]
	s_add_u32 m0, s76, 0x16000
	s_nop 0
	global_load_lds_dwordx4 v197, s[70:71]
	s_sub_u32 s68, s68, 0x80
	s_subb_u32 s69, s69, 0
	s_sub_u32 s70, s70, 0x80
	s_subb_u32 s71, s71, 0
	s_waitcnt vmcnt(6)
	s_waitcnt lgkmcnt(0)
	s_barrier
	v_mfma_f32_16x16x32_bf16 v[2:5], v[146:149], v[130:133], v[2:5]
	v_mfma_f32_16x16x32_bf16 v[6:9], v[150:153], v[130:133], v[6:9]
	v_mfma_f32_16x16x32_bf16 v[10:13], v[154:157], v[130:133], v[10:13]
	v_mfma_f32_16x16x32_bf16 v[14:17], v[158:161], v[130:133], v[14:17]
	v_mfma_f32_16x16x32_bf16 v[18:21], v[146:149], v[134:137], v[18:21]
	v_mfma_f32_16x16x32_bf16 v[22:25], v[150:153], v[134:137], v[22:25]
	v_mfma_f32_16x16x32_bf16 v[26:29], v[154:157], v[134:137], v[26:29]
	v_mfma_f32_16x16x32_bf16 v[30:33], v[158:161], v[134:137], v[30:33]
	v_mfma_f32_16x16x32_bf16 v[34:37], v[146:149], v[138:141], v[34:37]
	v_mfma_f32_16x16x32_bf16 v[38:41], v[150:153], v[138:141], v[38:41]
	v_mfma_f32_16x16x32_bf16 v[42:45], v[154:157], v[138:141], v[42:45]
	v_mfma_f32_16x16x32_bf16 v[46:49], v[158:161], v[138:141], v[46:49]
	v_mfma_f32_16x16x32_bf16 v[50:53], v[146:149], v[142:145], v[50:53]
	v_mfma_f32_16x16x32_bf16 v[54:57], v[150:153], v[142:145], v[54:57]
	v_mfma_f32_16x16x32_bf16 v[58:61], v[154:157], v[142:145], v[58:61]
	v_mfma_f32_16x16x32_bf16 v[62:65], v[158:161], v[142:145], v[62:65]
	v_mfma_f32_16x16x32_bf16 v[2:5], v[228:231], v[212:215], v[2:5]
	v_mfma_f32_16x16x32_bf16 v[6:9], v[232:235], v[212:215], v[6:9]
	v_mfma_f32_16x16x32_bf16 v[10:13], v[236:239], v[212:215], v[10:13]
	v_mfma_f32_16x16x32_bf16 v[14:17], v[240:243], v[212:215], v[14:17]
	v_mfma_f32_16x16x32_bf16 v[18:21], v[228:231], v[216:219], v[18:21]
	v_mfma_f32_16x16x32_bf16 v[22:25], v[232:235], v[216:219], v[22:25]
	v_mfma_f32_16x16x32_bf16 v[26:29], v[236:239], v[216:219], v[26:29]
	v_mfma_f32_16x16x32_bf16 v[30:33], v[240:243], v[216:219], v[30:33]
	v_mfma_f32_16x16x32_bf16 v[34:37], v[228:231], v[220:223], v[34:37]
	v_mfma_f32_16x16x32_bf16 v[38:41], v[232:235], v[220:223], v[38:41]
	v_mfma_f32_16x16x32_bf16 v[42:45], v[236:239], v[220:223], v[42:45]
	v_mfma_f32_16x16x32_bf16 v[46:49], v[240:243], v[220:223], v[46:49]
	v_mfma_f32_16x16x32_bf16 v[50:53], v[228:231], v[224:227], v[50:53]
	v_mfma_f32_16x16x32_bf16 v[54:57], v[232:235], v[224:227], v[54:57]
	v_mfma_f32_16x16x32_bf16 v[58:61], v[236:239], v[224:227], v[58:61]
	v_mfma_f32_16x16x32_bf16 v[62:65], v[240:243], v[224:227], v[62:65]
	s_barrier
	v_add_u32_e32 v204, 0x0, v200
	v_add_u32_e32 v205, 0x0, v202
	ds_read_b128 v[130:133], v204 offset:0
	ds_read_b128 v[134:137], v204 offset:2048
	ds_read_b128 v[138:141], v204 offset:4096
	ds_read_b128 v[142:145], v204 offset:6144
	ds_read_b128 v[146:149], v205 offset:0
	ds_read_b128 v[150:153], v205 offset:2048
	ds_read_b128 v[154:157], v205 offset:4096
	ds_read_b128 v[158:161], v205 offset:6144
	v_add_u32_e32 v204, 0x0, v201
	v_add_u32_e32 v205, 0x0, v203
	ds_read_b128 v[212:215], v204 offset:0
	ds_read_b128 v[216:219], v204 offset:2048
	ds_read_b128 v[220:223], v204 offset:4096
	ds_read_b128 v[224:227], v204 offset:6144
	ds_read_b128 v[228:231], v205 offset:0
	ds_read_b128 v[232:235], v205 offset:2048
	ds_read_b128 v[236:239], v205 offset:4096
	ds_read_b128 v[240:243], v205 offset:6144
	s_waitcnt vmcnt(0)
	s_waitcnt lgkmcnt(0)
	s_barrier
	v_mfma_f32_16x16x32_bf16 v[2:5], v[146:149], v[130:133], v[2:5]
	v_mfma_f32_16x16x32_bf16 v[6:9], v[150:153], v[130:133], v[6:9]
	v_mfma_f32_16x16x32_bf16 v[10:13], v[154:157], v[130:133], v[10:13]
	v_mfma_f32_16x16x32_bf16 v[14:17], v[158:161], v[130:133], v[14:17]
	v_mfma_f32_16x16x32_bf16 v[18:21], v[146:149], v[134:137], v[18:21]
	v_mfma_f32_16x16x32_bf16 v[22:25], v[150:153], v[134:137], v[22:25]
	v_mfma_f32_16x16x32_bf16 v[26:29], v[154:157], v[134:137], v[26:29]
	v_mfma_f32_16x16x32_bf16 v[30:33], v[158:161], v[134:137], v[30:33]
	v_mfma_f32_16x16x32_bf16 v[34:37], v[146:149], v[138:141], v[34:37]
	v_mfma_f32_16x16x32_bf16 v[38:41], v[150:153], v[138:141], v[38:41]
	v_mfma_f32_16x16x32_bf16 v[42:45], v[154:157], v[138:141], v[42:45]
	v_mfma_f32_16x16x32_bf16 v[46:49], v[158:161], v[138:141], v[46:49]
	v_mfma_f32_16x16x32_bf16 v[50:53], v[146:149], v[142:145], v[50:53]
	v_mfma_f32_16x16x32_bf16 v[54:57], v[150:153], v[142:145], v[54:57]
	v_mfma_f32_16x16x32_bf16 v[58:61], v[154:157], v[142:145], v[58:61]
	v_mfma_f32_16x16x32_bf16 v[62:65], v[158:161], v[142:145], v[62:65]
	v_mfma_f32_16x16x32_bf16 v[2:5], v[228:231], v[212:215], v[2:5]
	v_mfma_f32_16x16x32_bf16 v[6:9], v[232:235], v[212:215], v[6:9]
	v_mfma_f32_16x16x32_bf16 v[10:13], v[236:239], v[212:215], v[10:13]
	v_mfma_f32_16x16x32_bf16 v[14:17], v[240:243], v[212:215], v[14:17]
	v_mfma_f32_16x16x32_bf16 v[18:21], v[228:231], v[216:219], v[18:21]
	v_mfma_f32_16x16x32_bf16 v[22:25], v[232:235], v[216:219], v[22:25]
	v_mfma_f32_16x16x32_bf16 v[26:29], v[236:239], v[216:219], v[26:29]
	v_mfma_f32_16x16x32_bf16 v[30:33], v[240:243], v[216:219], v[30:33]
	v_mfma_f32_16x16x32_bf16 v[34:37], v[228:231], v[220:223], v[34:37]
	v_mfma_f32_16x16x32_bf16 v[38:41], v[232:235], v[220:223], v[38:41]
	v_mfma_f32_16x16x32_bf16 v[42:45], v[236:239], v[220:223], v[42:45]
	v_mfma_f32_16x16x32_bf16 v[46:49], v[240:243], v[220:223], v[46:49]
	v_mfma_f32_16x16x32_bf16 v[50:53], v[228:231], v[224:227], v[50:53]
	v_mfma_f32_16x16x32_bf16 v[54:57], v[232:235], v[224:227], v[54:57]
	v_mfma_f32_16x16x32_bf16 v[58:61], v[236:239], v[224:227], v[58:61]
	v_mfma_f32_16x16x32_bf16 v[62:65], v[240:243], v[224:227], v[62:65]
	s_barrier
	v_add_u32_e32 v204, 0xc000, v200
	v_add_u32_e32 v205, 0xc000, v202
	ds_read_b128 v[130:133], v204 offset:0
	ds_read_b128 v[134:137], v204 offset:2048
	ds_read_b128 v[138:141], v204 offset:4096
	ds_read_b128 v[142:145], v204 offset:6144
	ds_read_b128 v[146:149], v205 offset:0
	ds_read_b128 v[150:153], v205 offset:2048
	ds_read_b128 v[154:157], v205 offset:4096
	ds_read_b128 v[158:161], v205 offset:6144
	v_add_u32_e32 v204, 0xc000, v201
	v_add_u32_e32 v205, 0xc000, v203
	ds_read_b128 v[212:215], v204 offset:0
	ds_read_b128 v[216:219], v204 offset:2048
	ds_read_b128 v[220:223], v204 offset:4096
	ds_read_b128 v[224:227], v204 offset:6144
	ds_read_b128 v[228:231], v205 offset:0
	ds_read_b128 v[232:235], v205 offset:2048
	ds_read_b128 v[236:239], v205 offset:4096
	ds_read_b128 v[240:243], v205 offset:6144
	s_waitcnt lgkmcnt(0)
	s_barrier
	v_mfma_f32_16x16x32_bf16 v[2:5], v[146:149], v[130:133], v[2:5]
	v_mfma_f32_16x16x32_bf16 v[6:9], v[150:153], v[130:133], v[6:9]
	v_mfma_f32_16x16x32_bf16 v[10:13], v[154:157], v[130:133], v[10:13]
	v_mfma_f32_16x16x32_bf16 v[14:17], v[158:161], v[130:133], v[14:17]
	v_mfma_f32_16x16x32_bf16 v[18:21], v[146:149], v[134:137], v[18:21]
	v_mfma_f32_16x16x32_bf16 v[22:25], v[150:153], v[134:137], v[22:25]
	v_mfma_f32_16x16x32_bf16 v[26:29], v[154:157], v[134:137], v[26:29]
	v_mfma_f32_16x16x32_bf16 v[30:33], v[158:161], v[134:137], v[30:33]
	v_mfma_f32_16x16x32_bf16 v[34:37], v[146:149], v[138:141], v[34:37]
	v_mfma_f32_16x16x32_bf16 v[38:41], v[150:153], v[138:141], v[38:41]
	v_mfma_f32_16x16x32_bf16 v[42:45], v[154:157], v[138:141], v[42:45]
	v_mfma_f32_16x16x32_bf16 v[46:49], v[158:161], v[138:141], v[46:49]
	v_mfma_f32_16x16x32_bf16 v[50:53], v[146:149], v[142:145], v[50:53]
	v_mfma_f32_16x16x32_bf16 v[54:57], v[150:153], v[142:145], v[54:57]
	v_mfma_f32_16x16x32_bf16 v[58:61], v[154:157], v[142:145], v[58:61]
	v_mfma_f32_16x16x32_bf16 v[62:65], v[158:161], v[142:145], v[62:65]
	v_mfma_f32_16x16x32_bf16 v[2:5], v[228:231], v[212:215], v[2:5]
	v_mfma_f32_16x16x32_bf16 v[6:9], v[232:235], v[212:215], v[6:9]
	v_mfma_f32_16x16x32_bf16 v[10:13], v[236:239], v[212:215], v[10:13]
	v_mfma_f32_16x16x32_bf16 v[14:17], v[240:243], v[212:215], v[14:17]
	v_mfma_f32_16x16x32_bf16 v[18:21], v[228:231], v[216:219], v[18:21]
	v_mfma_f32_16x16x32_bf16 v[22:25], v[232:235], v[216:219], v[22:25]
	v_mfma_f32_16x16x32_bf16 v[26:29], v[236:239], v[216:219], v[26:29]
	v_mfma_f32_16x16x32_bf16 v[30:33], v[240:243], v[216:219], v[30:33]
	v_mfma_f32_16x16x32_bf16 v[34:37], v[228:231], v[220:223], v[34:37]
	v_mfma_f32_16x16x32_bf16 v[38:41], v[232:235], v[220:223], v[38:41]
	v_mfma_f32_16x16x32_bf16 v[42:45], v[236:239], v[220:223], v[42:45]
	v_mfma_f32_16x16x32_bf16 v[46:49], v[240:243], v[220:223], v[46:49]
	v_mfma_f32_16x16x32_bf16 v[50:53], v[228:231], v[224:227], v[50:53]
	v_mfma_f32_16x16x32_bf16 v[54:57], v[232:235], v[224:227], v[54:57]
	v_mfma_f32_16x16x32_bf16 v[58:61], v[236:239], v[224:227], v[58:61]
	v_mfma_f32_16x16x32_bf16 v[62:65], v[240:243], v[224:227], v[62:65]
